# decode units: window-state shift-copy stores non-temporal (nt)
# baseline (speedup 1.0000x reference)
; #define LAS __attribute__((address_space(3)))
; __device__ __forceinline__ unsigned cvt_pk_bf16(float lo, float hi) { unsigned r; asm volatile("v_cvt_pk_bf16_f32 %0, %1, %2" : "=v"(r) : "v"(lo), "v"(hi)); return r; }
; #define LDS_WAIT() asm volatile("s_waitcnt lgkmcnt(0)" ::: "memory")
; __device__ __forceinline__ void f32_k_issue(F32Tile& T, const float* kp, int lane) {
;     const float* kl = kp + (size_t)(lane >> 4) * 256 + (lane & 15) * 4;
; #pragma unroll
;     for (int i = 0; i < 16; ++i) T.x[i] = *(const f32x4*)(kl + (size_t)(4 * i) * 256);
; }
; template <int H> __device__ __forceinline__ void f32_k_commit(const F32Tile& T, LAS unsigned char* kb, int lane, float* kcopy, int skip) {
;     const int pc = lane & 15, rl = lane >> 4, c = pc >> 1;
;     float* kc = kcopy + (size_t)rl * 256 + pc * 4;
;     const unsigned keo = (unsigned)(c * 1024 + (pc & 1) * 8 + ((rl + c) & 7) * 16);
;     if (H == 0) LDS_WAIT();
; #pragma unroll
;     for (int i = 8 * H; i < 8 * H + 8; ++i) { u32x2 w; w.x = cvt_pk_bf16(T.x[i][0], T.x[i][1]); w.y = cvt_pk_bf16(T.x[i][2], T.x[i][3]);
;         *(LAS u32x2*)(kb + ((i & 1) ? (keo ^ 64u) : keo) + 128 * (i >> 1)) = w;
;         if (kcopy && 4 * i + rl >= skip) *(f32x4*)(kc + (size_t)(4 * i) * 256) = T.x[i]; }
;     if (H == 1) LDS_WAIT();
; }
; __device__ __forceinline__ void attn_decode_unit(const Params& P, const Ctx& C, int sg) {
;     ...
;     const float* sk = in6 + (size_t)seq * (512 * 256) + g * 64; const float* sv = in7 + (size_t)seq * (512 * 256) + g * 64;
;     float* ck = outp + O_SKW + (size_t)seq * (512 * 256) + g * 64; float* cv = outp + O_SVW + (size_t)seq * (512 * 256) + g * 64;
;     if (wave != 0) { const int j = wave;
;         F32_TILE_STEP(sk + (size_t)j * 64 * 256, sv + (size_t)j * 64 * 256, ck + ((ptrdiff_t)j * 64 - 4) * 256, cv + ((ptrdiff_t)j * 64 - 4) * 256, 0, 64 * j, qi + 1, 512 + qi, true, m_w, l_w, ow0, ow1); }
.LBB0_1240:
	s_ashr_i32 s94, s52, 2
	s_ashr_i32 s95, s94, 31
	s_lshl_b64 s[4:5], s[94:95], 19
	s_add_u32 s8, s12, s4
	s_addc_u32 s9, s13, s5
	s_lshl_b32 s12, s53, 8
	s_add_u32 s56, s8, s12
	s_addc_u32 s57, s9, 0
	s_add_u32 s8, s10, s4
	s_addc_u32 s9, s11, s5
	s_add_u32 s54, s8, s12
	s_addc_u32 s55, s9, 0
	s_add_u32 s2, s2, s4
	s_addc_u32 s3, s3, s5
	s_add_u32 s4, s2, s12
	s_addc_u32 s5, s3, 0
	s_add_u32 s2, s4, 0x8680000
	v_readlane_b32 s8, v254, 49
	s_addc_u32 s3, s5, 0
	v_readlane_b32 s9, v254, 50
	s_add_u32 s96, s4, 0xc680000
	v_and_b32_e32 v158, 15, v165
	v_cndmask_b32_e64 v0, 0, 1, s[8:9]
	s_addc_u32 s97, s5, 0
	v_cmp_ne_u32_e64 s[4:5], 1, v0
	s_andn2_b64 vcc, exec, s[8:9]
	v_bfe_u32 v159, v165, 1, 3
	s_waitcnt vmcnt(13)
	v_and_b32_e32 v122, 0xf0, v229
	v_lshlrev_b32_e32 v150, 4, v158
	v_writelane_b32 v254, s64, 23
	s_cbranch_vccnz .LBB0_1306
	v_readlane_b32 s14, v255, 25
	v_ashrrev_i32_e32 v116, 4, v165
	v_readlane_b32 s15, v255, 26
	s_add_u32 s8, s56, s14
	v_ashrrev_i32_e32 v117, 31, v116
	s_addc_u32 s9, s57, s15
	v_lshlrev_b64 v[114:115], 10, v[116:117]
	v_lshl_add_u64 v[2:3], s[8:9], 0, v[114:115]
	v_mov_b32_e32 v123, v1
	v_lshl_add_u64 v[2:3], v[2:3], 0, v[122:123]
	s_movk_i32 s10, 0x2000
	v_add_co_u32_e32 v4, vcc, s10, v2
	s_movk_i32 s11, 0x4000
	s_nop 0
	v_addc_co_u32_e32 v5, vcc, 0, v3, vcc
	global_load_dwordx4 v[106:109], v[4:5], off offset:-4096 nt
	global_load_dwordx4 v[102:105], v[4:5], off nt
	v_add_co_u32_e32 v4, vcc, s11, v2
	s_movk_i32 s12, 0x6000
	s_nop 0
	v_addc_co_u32_e32 v5, vcc, 0, v3, vcc
	global_load_dwordx4 v[98:101], v[4:5], off offset:-4096 nt
	global_load_dwordx4 v[94:97], v[4:5], off nt
	v_add_co_u32_e32 v4, vcc, s12, v2
	s_mov_b32 s8, 0x8000
	s_nop 0
	v_addc_co_u32_e32 v5, vcc, 0, v3, vcc
	global_load_dwordx4 v[82:85], v[4:5], off offset:-4096 nt
	global_load_dwordx4 v[62:65], v[4:5], off nt
	v_add_co_u32_e32 v4, vcc, s8, v2
	s_mov_b32 s8, 0xa000
	s_nop 0
	v_addc_co_u32_e32 v5, vcc, 0, v3, vcc
	global_load_dwordx4 v[54:57], v[4:5], off offset:-4096 nt
	global_load_dwordx4 v[30:33], v[4:5], off nt
	v_add_co_u32_e32 v4, vcc, s8, v2
	s_add_u32 s8, s54, s14
	s_nop 0
	v_addc_co_u32_e32 v5, vcc, 0, v3, vcc
	global_load_dwordx4 v[26:29], v[4:5], off offset:-4096 nt
	global_load_dwordx4 v[22:25], v[4:5], off nt
	v_add_co_u32_e32 v4, vcc, s45, v2
	s_addc_u32 s9, s55, s15
	s_nop 0
	v_addc_co_u32_e32 v5, vcc, 0, v3, vcc
	global_load_dwordx4 v[18:21], v[4:5], off offset:-4096 nt
	global_load_dwordx4 v[14:17], v[4:5], off nt
	v_add_co_u32_e32 v4, vcc, s47, v2
	v_lshl_add_u64 v[34:35], s[8:9], 0, v[114:115]
	s_nop 0
	v_addc_co_u32_e32 v5, vcc, 0, v3, vcc
	global_load_dwordx4 v[10:13], v[4:5], off offset:-4096 nt
	global_load_dwordx4 v[6:9], v[4:5], off nt
	v_add_co_u32_e32 v4, vcc, s62, v2
	v_lshl_add_u64 v[120:121], v[34:35], 0, v[122:123]
	s_nop 0
	v_addc_co_u32_e32 v5, vcc, 0, v3, vcc
	v_add_co_u32_e32 v34, vcc, s10, v120
	global_load_dwordx4 v[110:113], v[2:3], off nt
	s_nop 0
	global_load_dwordx4 v[2:5], v[4:5], off nt
	v_addc_co_u32_e32 v35, vcc, 0, v121, vcc
	global_load_dwordx4 v[90:93], v[120:121], off nt
	global_load_dwordx4 v[86:89], v[34:35], off offset:-4096 nt
	global_load_dwordx4 v[58:61], v[34:35], off nt
	v_add_co_u32_e32 v34, vcc, s11, v120
	s_movk_i32 s8, 0x7000
	s_nop 0
	v_addc_co_u32_e32 v35, vcc, 0, v121, vcc
	global_load_dwordx4 v[50:53], v[34:35], off offset:-4096 nt
	global_load_dwordx4 v[46:49], v[34:35], off nt
	v_add_co_u32_e32 v34, vcc, s12, v120
	v_mov_b32_e32 v151, v1
	s_nop 0
	v_addc_co_u32_e32 v35, vcc, 0, v121, vcc
	global_load_dwordx4 v[42:45], v[34:35], off offset:-4096 nt
	global_load_dwordx4 v[38:41], v[34:35], off nt
	v_add_co_u32_e32 v34, vcc, s8, v120
	s_add_u32 s8, s2, s14
	s_nop 0
	v_addc_co_u32_e32 v35, vcc, 0, v121, vcc
	global_load_dwordx4 v[34:37], v[34:35], off nt
	s_addc_u32 s9, s3, s15
	v_lshl_add_u64 v[118:119], s[8:9], 0, v[114:115]
	s_movk_i32 s8, 0xf000
	v_lshlrev_b32_e32 v117, 3, v165
	v_lshl_add_u64 v[124:125], v[118:119], 0, v[150:151]
	s_mov_b32 s9, -1
	v_and_b32_e32 v0, 8, v117
	v_lshl_add_u64 v[118:119], v[124:125], 0, s[8:9]
	v_lshl_or_b32 v0, v159, 10, v0
	v_add_lshl_u32 v123, v159, v116, 4
	s_movk_i32 s8, 0x70
	s_waitcnt lgkmcnt(0)
	v_and_or_b32 v0, v123, s8, v0
	v_add_u32_e32 v123, s33, v0
	v_cmp_lt_i32_e64 s[8:9], -1, v116
	s_waitcnt vmcnt(9)
	v_cvt_pk_bf16_f32 v126, v110, v111
	v_cvt_pk_bf16_f32 v127, v112, v113
	ds_write_b64 v123, v[126:127]
	s_and_saveexec_b64 s[10:11], s[8:9]
	s_cbranch_execz .LBB0_1243
	global_store_dwordx4 v[118:119], v[110:113], off nt
.LBB0_1243:
	s_or_b64 exec, exec, s[10:11]
	v_xor_b32_e32 v0, 64, v0
	v_add_u32_e32 v0, s33, v0
	v_cmp_lt_i32_e64 s[10:11], -5, v116
	v_cvt_pk_bf16_f32 v110, v106, v107
	v_cvt_pk_bf16_f32 v111, v108, v109
	ds_write_b64 v0, v[110:111]
	s_and_saveexec_b64 s[12:13], s[10:11]
	s_cbranch_execz .LBB0_1245
	global_store_dwordx4 v[124:125], v[106:109], off nt
.LBB0_1245:
	s_or_b64 exec, exec, s[12:13]
	v_cmp_lt_i32_e64 s[12:13], -9, v116
	v_cvt_pk_bf16_f32 v106, v102, v103
	v_cvt_pk_bf16_f32 v107, v104, v105
	ds_write_b64 v123, v[106:107] offset:128
	s_and_saveexec_b64 s[14:15], s[12:13]
	s_cbranch_execz .LBB0_1247
	v_add_co_u32_e32 v106, vcc, 0x2000, v118
	s_nop 1
	v_addc_co_u32_e32 v107, vcc, 0, v119, vcc
	global_store_dwordx4 v[106:107], v[102:105], off nt
.LBB0_1247:
	s_or_b64 exec, exec, s[14:15]
	v_cmp_lt_i32_e64 s[14:15], -13, v116
	v_cvt_pk_bf16_f32 v102, v98, v99
	v_cvt_pk_bf16_f32 v103, v100, v101
	ds_write_b64 v0, v[102:103] offset:128
	s_and_saveexec_b64 s[16:17], s[14:15]
	s_cbranch_execz .LBB0_1249
	v_add_co_u32_e32 v102, vcc, 0x3000, v118
	s_nop 1
	v_addc_co_u32_e32 v103, vcc, 0, v119, vcc
	global_store_dwordx4 v[102:103], v[98:101], off nt
; #define LAS __attribute__((address_space(3)))
; __device__ __forceinline__ unsigned cvt_pk_bf16(float lo, float hi) { unsigned r; asm volatile("v_cvt_pk_bf16_f32 %0, %1, %2" : "=v"(r) : "v"(lo), "v"(hi)); return r; }
; #define LDS_WAIT() asm volatile("s_waitcnt lgkmcnt(0)" ::: "memory")
; template <int H> __device__ __forceinline__ void f32_k_commit(const F32Tile& T, LAS unsigned char* kb, int lane, float* kcopy, int skip) {
;     const int pc = lane & 15, rl = lane >> 4, c = pc >> 1;
;     float* kc = kcopy + (size_t)rl * 256 + pc * 4;
;     const unsigned keo = (unsigned)(c * 1024 + (pc & 1) * 8 + ((rl + c) & 7) * 16);
;     if (H == 0) LDS_WAIT();
; #pragma unroll
;     for (int i = 8 * H; i < 8 * H + 8; ++i) { u32x2 w; w.x = cvt_pk_bf16(T.x[i][0], T.x[i][1]); w.y = cvt_pk_bf16(T.x[i][2], T.x[i][3]);
;         *(LAS u32x2*)(kb + ((i & 1) ? (keo ^ 64u) : keo) + 128 * (i >> 1)) = w;
;         if (kcopy && 4 * i + rl >= skip) *(f32x4*)(kc + (size_t)(4 * i) * 256) = T.x[i]; }
;     if (H == 1) LDS_WAIT();
; }
; __device__ __forceinline__ void f32_v_issue(F32Half& T, const float* vp, int lane, int h) {
;     const float* vl = vp + (size_t)(lane >> 4) * 256 + (lane & 15) * 4;
; #pragma unroll
;     for (int i = 0; i < 8; ++i) T.x[i] = *(const f32x4*)(vl + (size_t)(4 * (8 * h + i)) * 256);
; }
.LBB0_1249:
	s_or_b64 exec, exec, s[16:17]
	s_movk_i32 s16, 0xffef
	v_cmp_lt_i32_e64 s[16:17], s16, v116
	v_cvt_pk_bf16_f32 v98, v94, v95
	v_cvt_pk_bf16_f32 v99, v96, v97
	ds_write_b64 v123, v[98:99] offset:256
	s_and_saveexec_b64 s[18:19], s[16:17]
	s_cbranch_execz .LBB0_1251
	v_add_co_u32_e32 v98, vcc, 0x4000, v118
	s_nop 1
	v_addc_co_u32_e32 v99, vcc, 0, v119, vcc
	global_store_dwordx4 v[98:99], v[94:97], off nt
.LBB0_1251:
	s_or_b64 exec, exec, s[18:19]
	s_movk_i32 s18, 0xffeb
	v_cmp_lt_i32_e64 s[18:19], s18, v116
	v_cvt_pk_bf16_f32 v94, v82, v83
	v_cvt_pk_bf16_f32 v95, v84, v85
	ds_write_b64 v0, v[94:95] offset:256
	s_and_saveexec_b64 s[20:21], s[18:19]
	s_cbranch_execz .LBB0_1253
	v_add_co_u32_e32 v94, vcc, 0x5000, v118
	s_nop 1
	v_addc_co_u32_e32 v95, vcc, 0, v119, vcc
	global_store_dwordx4 v[94:95], v[82:85], off nt
.LBB0_1253:
	s_or_b64 exec, exec, s[20:21]
	s_movk_i32 s20, 0xffe7
	v_cmp_lt_i32_e64 s[20:21], s20, v116
	v_cvt_pk_bf16_f32 v82, v62, v63
	v_cvt_pk_bf16_f32 v83, v64, v65
	ds_write_b64 v123, v[82:83] offset:384
	s_and_saveexec_b64 s[22:23], s[20:21]
	s_cbranch_execz .LBB0_1255
	v_add_co_u32_e32 v82, vcc, 0x6000, v118
	s_nop 1
	v_addc_co_u32_e32 v83, vcc, 0, v119, vcc
	global_store_dwordx4 v[82:83], v[62:65], off nt
.LBB0_1255:
	s_or_b64 exec, exec, s[22:23]
	s_movk_i32 s22, 0xffe3
	v_cmp_lt_i32_e64 s[22:23], s22, v116
	v_cvt_pk_bf16_f32 v62, v54, v55
	v_cvt_pk_bf16_f32 v63, v56, v57
	ds_write_b64 v0, v[62:63] offset:384
	s_and_saveexec_b64 s[24:25], s[22:23]
	s_cbranch_execz .LBB0_1257
	v_add_co_u32_e32 v62, vcc, 0x7000, v118
	s_nop 1
	v_addc_co_u32_e32 v63, vcc, 0, v119, vcc
	global_store_dwordx4 v[62:63], v[54:57], off nt
.LBB0_1257:
	s_or_b64 exec, exec, s[24:25]
	s_nop 0
	v_add_co_u32_e32 v54, vcc, 0x8000, v120
	s_movk_i32 s24, 0xffdf
	s_nop 0
	v_addc_co_u32_e32 v55, vcc, 0, v121, vcc
	v_add_co_u32_e32 v56, vcc, 0x9000, v120
	v_cmp_lt_i32_e64 s[24:25], s24, v116
	s_nop 0
	v_addc_co_u32_e32 v57, vcc, 0, v121, vcc
	global_load_dwordx4 v[110:113], v[54:55], off nt
	global_load_dwordx4 v[106:109], v[56:57], off nt
	v_add_co_u32_e32 v54, vcc, 0xa000, v120
	s_nop 1
	v_addc_co_u32_e32 v55, vcc, 0, v121, vcc
	v_add_co_u32_e32 v56, vcc, 0xb000, v120
	s_nop 1
	v_addc_co_u32_e32 v57, vcc, 0, v121, vcc
	global_load_dwordx4 v[102:105], v[54:55], off nt
	global_load_dwordx4 v[98:101], v[56:57], off nt
	v_add_co_u32_e32 v54, vcc, 0xc000, v120
	s_nop 1
	v_addc_co_u32_e32 v55, vcc, 0, v121, vcc
	v_add_co_u32_e32 v56, vcc, 0xd000, v120
	s_nop 1
	v_addc_co_u32_e32 v57, vcc, 0, v121, vcc
	global_load_dwordx4 v[94:97], v[54:55], off nt
	global_load_dwordx4 v[82:85], v[56:57], off nt
	v_add_co_u32_e32 v54, vcc, 0xe000, v120
	s_nop 1
	v_addc_co_u32_e32 v55, vcc, 0, v121, vcc
	v_add_co_u32_e32 v56, vcc, 0xf000, v120
	s_nop 1
	v_addc_co_u32_e32 v57, vcc, 0, v121, vcc
	global_load_dwordx4 v[62:65], v[54:55], off nt
	s_nop 0
	global_load_dwordx4 v[54:57], v[56:57], off nt
	v_cvt_pk_bf16_f32 v120, v30, v31
	v_cvt_pk_bf16_f32 v121, v32, v33
	ds_write_b64 v123, v[120:121] offset:512
	s_and_saveexec_b64 s[26:27], s[24:25]
	s_cbranch_execz .LBB0_1259
	v_add_co_u32_e32 v120, vcc, 0x8000, v118
	s_nop 1
	v_addc_co_u32_e32 v121, vcc, 0, v119, vcc
	global_store_dwordx4 v[120:121], v[30:33], off nt
.LBB0_1259:
	s_or_b64 exec, exec, s[26:27]
	s_movk_i32 s26, 0xffdb
	v_cmp_lt_i32_e64 s[26:27], s26, v116
	v_cvt_pk_bf16_f32 v30, v26, v27
	v_cvt_pk_bf16_f32 v31, v28, v29
	ds_write_b64 v0, v[30:31] offset:512
	s_and_saveexec_b64 s[28:29], s[26:27]
	s_cbranch_execz .LBB0_1261
	v_add_co_u32_e32 v30, vcc, 0x9000, v118
	s_nop 1
	v_addc_co_u32_e32 v31, vcc, 0, v119, vcc
	global_store_dwordx4 v[30:31], v[26:29], off nt
.LBB0_1261:
	s_or_b64 exec, exec, s[28:29]
	s_movk_i32 s28, 0xffd7
	v_cmp_lt_i32_e64 s[28:29], s28, v116
	v_cvt_pk_bf16_f32 v26, v22, v23
	v_cvt_pk_bf16_f32 v27, v24, v25
	ds_write_b64 v123, v[26:27] offset:640
	s_and_saveexec_b64 s[30:31], s[28:29]
	s_cbranch_execz .LBB0_1263
	v_add_co_u32_e32 v26, vcc, 0xa000, v118
	s_nop 1
	v_addc_co_u32_e32 v27, vcc, 0, v119, vcc
	global_store_dwordx4 v[26:27], v[22:25], off nt
.LBB0_1263:
	s_or_b64 exec, exec, s[30:31]
	s_movk_i32 s30, 0xffd3
	v_cmp_lt_i32_e64 s[30:31], s30, v116
	v_cvt_pk_bf16_f32 v22, v18, v19
	v_cvt_pk_bf16_f32 v23, v20, v21
	ds_write_b64 v0, v[22:23] offset:640
	s_and_saveexec_b64 s[34:35], s[30:31]
	s_cbranch_execz .LBB0_1265
	v_add_co_u32_e32 v22, vcc, 0xb000, v118
	s_nop 1
	v_addc_co_u32_e32 v23, vcc, 0, v119, vcc
	global_store_dwordx4 v[22:23], v[18:21], off nt
.LBB0_1265:
	s_or_b64 exec, exec, s[34:35]
	s_movk_i32 s34, 0xffcf
	v_cmp_lt_i32_e64 s[34:35], s34, v116
	v_cvt_pk_bf16_f32 v18, v14, v15
	v_cvt_pk_bf16_f32 v19, v16, v17
	ds_write_b64 v123, v[18:19] offset:768
	s_and_saveexec_b64 s[36:37], s[34:35]
	s_cbranch_execz .LBB0_1267
	v_add_co_u32_e32 v18, vcc, 0xc000, v118
	s_nop 1
	v_addc_co_u32_e32 v19, vcc, 0, v119, vcc
	global_store_dwordx4 v[18:19], v[14:17], off nt
.LBB0_1267:
	s_or_b64 exec, exec, s[36:37]
	s_movk_i32 s36, 0xffcb
	v_cmp_lt_i32_e64 s[36:37], s36, v116
	v_cvt_pk_bf16_f32 v14, v10, v11
	v_cvt_pk_bf16_f32 v15, v12, v13
	ds_write_b64 v0, v[14:15] offset:768
	s_and_saveexec_b64 s[38:39], s[36:37]
	s_cbranch_execz .LBB0_1269
	v_add_co_u32_e32 v14, vcc, 0xd000, v118
	s_nop 1
	v_addc_co_u32_e32 v15, vcc, 0, v119, vcc
	global_store_dwordx4 v[14:15], v[10:13], off nt
.LBB0_1269:
	s_or_b64 exec, exec, s[38:39]
	s_movk_i32 s38, 0xffc7
	v_cmp_lt_i32_e64 s[38:39], s38, v116
	v_cvt_pk_bf16_f32 v10, v6, v7
	v_cvt_pk_bf16_f32 v11, v8, v9
	ds_write_b64 v123, v[10:11] offset:896
	s_and_saveexec_b64 s[40:41], s[38:39]
	s_cbranch_execz .LBB0_1271
	v_add_co_u32_e32 v10, vcc, 0xe000, v118
	s_nop 1
	v_addc_co_u32_e32 v11, vcc, 0, v119, vcc
	global_store_dwordx4 v[10:11], v[6:9], off nt
; #define LAS __attribute__((address_space(3)))
; __device__ __forceinline__ unsigned cvt_pk_bf16(float lo, float hi) { unsigned r; asm volatile("v_cvt_pk_bf16_f32 %0, %1, %2" : "=v"(r) : "v"(lo), "v"(hi)); return r; }
; __device__ __forceinline__ int crow(int r, int hi) { return (r & 3) + 8 * (r >> 2) + 4 * hi; }
; #define LDS_WAIT() asm volatile("s_waitcnt lgkmcnt(0)" ::: "memory")
; __device__ __forceinline__ void qk_tile_sw(const LAS unsigned char* kb, const bf16x8 (&qr)[4], f32x16& s0, f32x16& s1, int r32, int hi) {
;     f32x16 a = {0.f, 0.f, 0.f, 0.f, 0.f, 0.f, 0.f, 0.f, 0.f, 0.f, 0.f, 0.f, 0.f, 0.f, 0.f, 0.f}, b = a;
;     const LAS unsigned char* kp = kb + hi * 1024 + (r32 & ~7) * 16;
; #pragma unroll
;     for (int d0 = 0; d0 < 4; ++d0) { const int lo = (r32 + 2 * d0 + hi) & 7;
;         const bf16x8 k0 = *(const LAS bf16x8*)(kp + d0 * 2048 + lo * 16), k1 = *(const LAS bf16x8*)(kp + d0 * 2048 + lo * 16 + 512);
;         a = MFMA32(k0, qr[d0], a); b = MFMA32(k1, qr[d0], b);
;     }
;     s0 = a; s1 = b;
; }
; __device__ __forceinline__ void qk_tile(const LAS unsigned char* kb, const bf16x8 (&qr)[4], f32x16& s0, f32x16& s1, int r32, int hi) {
;     const LAS unsigned char* kp = kb + hi * 1024 + r32 * 16;
;     f32x16 a = F16Z, b = F16Z;
; #pragma unroll
;     for (int d0 = 0; d0 < 4; ++d0) {
;         const bf16x8 k0 = *(const LAS bf16x8*)(kp + d0 * 2048), k1 = *(const LAS bf16x8*)(kp + d0 * 2048 + 512);
;         a = MFMA32(k0, qr[d0], a); b = MFMA32(k1, qr[d0], b);
;     }
;     s0 = a; s1 = b;
; }
; __device__ __forceinline__ void mask_tile(f32x16& s0, f32x16& s1, int key0, int klo, int khi, bool en, int hi) {
; #pragma unroll
;     for (int r = 0; r < 16; ++r) { const int k = key0 + crow(r, hi);
;         if (!(en && k >= klo && k <= khi)) s0[r] = NEG_INF;
;         if (!(en && k + 32 >= klo && k + 32 <= khi)) s1[r] = NEG_INF; }
; }
; template <int H> __device__ __forceinline__ void f32_k_commit(const F32Tile& T, LAS unsigned char* kb, int lane, float* kcopy, int skip) {
;     ...
;     for (int i = 8 * H; i < 8 * H + 8; ++i) { u32x2 w; w.x = cvt_pk_bf16(T.x[i][0], T.x[i][1]); w.y = cvt_pk_bf16(T.x[i][2], T.x[i][3]);
;         *(LAS u32x2*)(kb + ((i & 1) ? (keo ^ 64u) : keo) + 128 * (i >> 1)) = w;
;         if (kcopy && 4 * i + rl >= skip) *(f32x4*)(kc + (size_t)(4 * i) * 256) = T.x[i]; }
;     if (H == 1) LDS_WAIT();
; }
.LBB0_1271:
	s_or_b64 exec, exec, s[40:41]
	s_movk_i32 s40, 0xffc3
	v_cmp_lt_i32_e64 s[40:41], s40, v116
	s_waitcnt vmcnt(16)
	v_cvt_pk_bf16_f32 v6, v2, v3
	v_cvt_pk_bf16_f32 v7, v4, v5
	ds_write_b64 v0, v[6:7] offset:896
	s_and_saveexec_b64 s[42:43], s[40:41]
	s_cbranch_execz .LBB0_1273
	v_add_co_u32_e32 v6, vcc, 0xf000, v118
	s_nop 1
	v_addc_co_u32_e32 v7, vcc, 0, v119, vcc
	global_store_dwordx4 v[6:7], v[2:5], off nt
.LBB0_1273:
	s_or_b64 exec, exec, s[42:43]
	v_lshlrev_b32_e32 v0, 4, v228
	v_and_b32_e32 v0, 0x180, v0
	v_add_lshl_u32 v123, v166, v228, 4
	v_add3_u32 v0, s33, v168, v0
	v_and_b32_e32 v124, 0x70, v123
	s_waitcnt lgkmcnt(0)
	v_add_u32_e32 v18, v0, v124
	ds_read_b128 v[2:5], v18
	v_add_u32_e32 v22, 32, v123
	v_and_b32_e32 v22, 0x70, v22
	v_add_u32_e32 v125, v0, v22
	ds_read_b128 v[118:121], v125 offset:2048
	ds_read_b128 v[18:21], v18 offset:512
	s_waitcnt lgkmcnt(2)
	v_mfma_f32_32x32x16_bf16 v[2:17], v[2:5], v[74:77], 0
	v_xad_u32 v124, v124, 64, v0
	v_add_u32_e32 v123, 0x60, v123
	v_and_b32_e32 v123, 0x70, v123
	v_add_u32_e32 v0, v0, v123
	v_lshl_add_u32 v136, v166, 2, s51
	v_cmp_gt_i32_e32 vcc, v136, v167
	v_lshlrev_b32_e32 v135, 2, v158
	s_waitcnt lgkmcnt(1)
	v_mfma_f32_32x32x16_bf16 v[2:17], v[118:121], v[66:69], v[2:17]
	ds_read_b128 v[118:121], v125 offset:2560
	s_waitcnt lgkmcnt(1)
	v_mfma_f32_32x32x16_bf16 v[18:33], v[18:21], v[74:77], 0
	s_waitcnt lgkmcnt(0)
	v_mfma_f32_32x32x16_bf16 v[18:33], v[118:121], v[66:69], v[18:33]
	ds_read_b128 v[118:121], v124 offset:4096
	s_waitcnt lgkmcnt(0)
	v_mfma_f32_32x32x16_bf16 v[2:17], v[118:121], v[70:73], v[2:17]
	ds_read_b128 v[118:121], v124 offset:4608
	ds_read_b128 v[124:127], v0 offset:6656
	s_waitcnt lgkmcnt(1)
	v_mfma_f32_32x32x16_bf16 v[18:33], v[118:121], v[70:73], v[18:33]
	ds_read_b128 v[118:121], v0 offset:6144
	v_or_b32_e32 v0, 0x200, v167
	v_cmp_le_i32_e64 s[42:43], v136, v0
	s_and_b64 vcc, vcc, s[42:43]
	s_waitcnt lgkmcnt(0)
	s_waitcnt lgkmcnt(0)
	v_mfma_f32_32x32x16_bf16 v[2:17], v[118:121], v[78:81], v[2:17]
	v_mfma_f32_32x32x16_bf16 v[18:33], v[124:127], v[78:81], v[18:33]
	s_nop 10
	v_cndmask_b32_e32 v131, v219, v2, vcc
	v_add_u32_e32 v2, 32, v136
	v_cmp_le_i32_e32 vcc, v2, v167
	v_cmp_gt_i32_e64 s[42:43], v2, v0
	s_or_b64 vcc, vcc, s[42:43]
	v_cmp_lt_i32_e64 s[42:43], v136, v0
	v_add_u32_e32 v2, 33, v136
	v_cndmask_b32_e32 v134, v18, v219, vcc
	v_cmp_ge_i32_e32 vcc, v136, v167
	s_and_b64 vcc, vcc, s[42:43]
	v_cmp_gt_i32_e64 s[42:43], v2, v0
	v_cndmask_b32_e32 v132, v219, v3, vcc
	v_cmp_le_i32_e32 vcc, v2, v167
	s_or_b64 vcc, vcc, s[42:43]
	v_or_b32_e32 v2, 2, v136
	v_cndmask_b32_e32 v133, v19, v219, vcc
	v_cmp_gt_i32_e32 vcc, v2, v167
	v_cmp_le_i32_e64 s[42:43], v2, v0
	s_and_b64 vcc, vcc, s[42:43]
	v_add_u32_e32 v2, 34, v136
	v_cndmask_b32_e32 v129, v219, v4, vcc
	v_cmp_le_i32_e32 vcc, v2, v167
	v_cmp_gt_i32_e64 s[42:43], v2, v0
	s_or_b64 vcc, vcc, s[42:43]
	v_or_b32_e32 v2, 3, v136
	v_cndmask_b32_e32 v130, v20, v219, vcc
	v_cmp_gt_i32_e32 vcc, v2, v167
	v_cmp_le_i32_e64 s[42:43], v2, v0
	s_and_b64 vcc, vcc, s[42:43]
	v_add_u32_e32 v2, 35, v136
	v_cndmask_b32_e32 v127, v219, v5, vcc
	v_cmp_le_i32_e32 vcc, v2, v167
	v_cmp_gt_i32_e64 s[42:43], v2, v0
	s_or_b64 vcc, vcc, s[42:43]
	v_add_u32_e32 v2, 8, v136
	v_cndmask_b32_e32 v128, v21, v219, vcc
	v_cmp_gt_i32_e32 vcc, v2, v167
	v_cmp_le_i32_e64 s[42:43], v2, v0
	s_and_b64 vcc, vcc, s[42:43]
	v_add_u32_e32 v2, 40, v136
	v_cndmask_b32_e32 v125, v219, v6, vcc
	v_cmp_le_i32_e32 vcc, v2, v167
	v_cmp_gt_i32_e64 s[42:43], v2, v0
	s_or_b64 vcc, vcc, s[42:43]
	v_add_u32_e32 v2, 9, v136
	v_cndmask_b32_e32 v126, v22, v219, vcc
	v_cmp_gt_i32_e32 vcc, v2, v167
	v_cmp_le_i32_e64 s[42:43], v2, v0
	s_and_b64 vcc, vcc, s[42:43]
	v_add_u32_e32 v2, 41, v136
	v_cndmask_b32_e32 v123, v219, v7, vcc
	v_cmp_le_i32_e32 vcc, v2, v167
	v_cmp_gt_i32_e64 s[42:43], v2, v0
	s_or_b64 vcc, vcc, s[42:43]
	v_add_u32_e32 v2, 10, v136
	v_cndmask_b32_e32 v124, v23, v219, vcc
	v_cmp_gt_i32_e32 vcc, v2, v167
	v_cmp_le_i32_e64 s[42:43], v2, v0
	s_and_b64 vcc, vcc, s[42:43]
	v_add_u32_e32 v2, 42, v136
	v_cndmask_b32_e32 v120, v219, v8, vcc
	v_cmp_le_i32_e32 vcc, v2, v167
	v_cmp_gt_i32_e64 s[42:43], v2, v0
	s_or_b64 vcc, vcc, s[42:43]
	v_add_u32_e32 v2, 11, v136
	v_cndmask_b32_e32 v121, v24, v219, vcc
	v_cmp_gt_i32_e32 vcc, v2, v167
	v_cmp_le_i32_e64 s[42:43], v2, v0
	s_and_b64 vcc, vcc, s[42:43]
	v_add_u32_e32 v2, 43, v136
	v_cndmask_b32_e32 v118, v219, v9, vcc
	v_cmp_le_i32_e32 vcc, v2, v167
	v_cmp_gt_i32_e64 s[42:43], v2, v0
	s_or_b64 vcc, vcc, s[42:43]
	v_add_u32_e32 v2, 16, v136
	v_cndmask_b32_e32 v119, v25, v219, vcc
	v_cmp_gt_i32_e32 vcc, v2, v167
	v_cmp_le_i32_e64 s[42:43], v2, v0
	s_and_b64 vcc, vcc, s[42:43]
	v_add_u32_e32 v2, 48, v136
	v_cndmask_b32_e32 v24, v219, v10, vcc
	v_cmp_le_i32_e32 vcc, v2, v167
	v_cmp_gt_i32_e64 s[42:43], v2, v0
	s_or_b64 vcc, vcc, s[42:43]
	v_add_u32_e32 v2, 17, v136
	v_cndmask_b32_e32 v25, v26, v219, vcc
	v_cmp_gt_i32_e32 vcc, v2, v167
	v_cmp_le_i32_e64 s[42:43], v2, v0
	s_and_b64 vcc, vcc, s[42:43]
	v_add_u32_e32 v2, 49, v136
	v_cndmask_b32_e32 v22, v219, v11, vcc
	v_cmp_le_i32_e32 vcc, v2, v167
	v_cmp_gt_i32_e64 s[42:43], v2, v0
	s_or_b64 vcc, vcc, s[42:43]
	v_add_u32_e32 v2, 18, v136
	v_cndmask_b32_e32 v23, v27, v219, vcc
	v_cmp_gt_i32_e32 vcc, v2, v167
	v_cmp_le_i32_e64 s[42:43], v2, v0
	s_and_b64 vcc, vcc, s[42:43]
	v_add_u32_e32 v2, 50, v136
	v_cndmask_b32_e32 v20, v219, v12, vcc
	v_cmp_le_i32_e32 vcc, v2, v167
	v_cmp_gt_i32_e64 s[42:43], v2, v0
	s_or_b64 vcc, vcc, s[42:43]
	v_add_u32_e32 v2, 19, v136
	v_cndmask_b32_e32 v21, v28, v219, vcc
	v_cmp_gt_i32_e32 vcc, v2, v167
	v_cmp_le_i32_e64 s[42:43], v2, v0
; #define LAS __attribute__((address_space(3)))
; __device__ __forceinline__ unsigned cvt_pk_bf16(float lo, float hi) { unsigned r; asm volatile("v_cvt_pk_bf16_f32 %0, %1, %2" : "=v"(r) : "v"(lo), "v"(hi)); return r; }
; __device__ __forceinline__ int crow(int r, int hi) { return (r & 3) + 8 * (r >> 2) + 4 * hi; }
; __device__ __forceinline__ void mask_tile(f32x16& s0, f32x16& s1, int key0, int klo, int khi, bool en, int hi) {
; #pragma unroll
;     for (int r = 0; r < 16; ++r) { const int k = key0 + crow(r, hi);
;         if (!(en && k >= klo && k <= khi)) s0[r] = NEG_INF;
;         if (!(en && k + 32 >= klo && k + 32 <= khi)) s1[r] = NEG_INF; }
; }
; __device__ __forceinline__ float half_swap_max(float m) { auto rr = __builtin_amdgcn_permlane32_swap(__float_as_uint(m), __float_as_uint(m), false, false); return fmaxf(__uint_as_float(rr[0]), __uint_as_float(rr[1])); }
; __device__ __forceinline__ float half_swap_sum(float m) { auto rr = __builtin_amdgcn_permlane32_swap(__float_as_uint(m), __float_as_uint(m), false, false); return __uint_as_float(rr[0]) + __uint_as_float(rr[1]); }
; __device__ __forceinline__ float tile_max(const f32x16& s0, const f32x16& s1) {
;     float m = fmaxf(s0[0], s1[0]);
; #pragma unroll
;     for (int r = 1; r < 16; ++r) m = fmaxf(m, fmaxf(s0[r], s1[r]));
;     return half_swap_max(m);
; }
; __device__ __forceinline__ void f32_v_commit(const F32Half& T, LAS unsigned char* vb, int lane, float* vcopy, int skip, int h) {
;     const int pc = lane & 15, rl = lane >> 4;
;     LAS unsigned char* vd = vb + (pc >> 3) * 4096 + rl * 64 + (pc & 7) * 8; float* vc = vcopy + (size_t)rl * 256 + pc * 4;
; #pragma unroll
;     for (int i = 0; i < 8; ++i) { const int ri = 4 * (8 * h + i); u32x2 w; w.x = cvt_pk_bf16(T.x[i][0], T.x[i][1]); w.y = cvt_pk_bf16(T.x[i][2], T.x[i][3]);
;         *(LAS u32x2*)(vd + ri * 64) = w;
;         if (vcopy && ri + rl >= skip) *(f32x4*)(vc + (size_t)ri * 256) = T.x[i]; }
	s_and_b64 vcc, vcc, s[42:43]
	v_add_u32_e32 v2, 51, v136
	v_cndmask_b32_e32 v18, v219, v13, vcc
	v_cmp_le_i32_e32 vcc, v2, v167
	v_cmp_gt_i32_e64 s[42:43], v2, v0
	s_or_b64 vcc, vcc, s[42:43]
	v_add_u32_e32 v2, 24, v136
	v_cndmask_b32_e32 v19, v29, v219, vcc
	v_cmp_gt_i32_e32 vcc, v2, v167
	v_cmp_le_i32_e64 s[42:43], v2, v0
	s_and_b64 vcc, vcc, s[42:43]
	v_add_u32_e32 v2, 56, v136
	v_cndmask_b32_e32 v12, v219, v14, vcc
	v_cmp_le_i32_e32 vcc, v2, v167
	v_cmp_gt_i32_e64 s[42:43], v2, v0
	s_or_b64 vcc, vcc, s[42:43]
	v_add_u32_e32 v2, 25, v136
	v_cndmask_b32_e32 v13, v30, v219, vcc
	v_cmp_gt_i32_e32 vcc, v2, v167
	v_cmp_le_i32_e64 s[42:43], v2, v0
	s_and_b64 vcc, vcc, s[42:43]
	v_add_u32_e32 v2, 57, v136
	v_cndmask_b32_e32 v6, v219, v15, vcc
	v_cmp_le_i32_e32 vcc, v2, v167
	v_cmp_gt_i32_e64 s[42:43], v2, v0
	s_or_b64 vcc, vcc, s[42:43]
	v_add_u32_e32 v2, 26, v136
	v_cndmask_b32_e32 v7, v31, v219, vcc
	v_cmp_gt_i32_e32 vcc, v2, v167
	v_cmp_le_i32_e64 s[42:43], v2, v0
	s_and_b64 vcc, vcc, s[42:43]
	v_add_u32_e32 v2, 58, v136
	v_cndmask_b32_e32 v8, v219, v16, vcc
	v_cmp_le_i32_e32 vcc, v2, v167
	v_cmp_gt_i32_e64 s[42:43], v2, v0
	s_or_b64 vcc, vcc, s[42:43]
	v_add_u32_e32 v2, 27, v136
	v_cndmask_b32_e32 v9, v32, v219, vcc
	v_cmp_gt_i32_e32 vcc, v2, v167
	v_cmp_le_i32_e64 s[42:43], v2, v0
	s_and_b64 vcc, vcc, s[42:43]
	v_add_u32_e32 v2, 59, v136
	v_cndmask_b32_e32 v10, v219, v17, vcc
	v_cmp_le_i32_e32 vcc, v2, v167
	v_cmp_gt_i32_e64 s[42:43], v2, v0
	v_max_f32_e32 v0, v133, v133
	v_max_f32_e32 v2, v132, v132
	v_max_f32_e32 v0, v2, v0
	v_max_f32_e32 v2, v130, v130
	v_max_f32_e32 v3, v129, v129
	v_max_f32_e32 v2, v3, v2
	v_max_f32_e32 v3, v128, v128
	v_max_f32_e32 v4, v127, v127
	v_max3_f32 v0, v131, v134, v0
	v_max_f32_e32 v3, v4, v3
	v_max3_f32 v0, v0, v2, v3
	v_max_f32_e32 v2, v126, v126
	v_max_f32_e32 v3, v125, v125
	v_max_f32_e32 v2, v3, v2
	v_max_f32_e32 v3, v124, v124
	v_max_f32_e32 v4, v123, v123
	v_max_f32_e32 v3, v4, v3
	v_max3_f32 v0, v0, v2, v3
	v_max_f32_e32 v2, v121, v121
	v_max_f32_e32 v3, v120, v120
	v_max_f32_e32 v2, v3, v2
	v_max_f32_e32 v3, v119, v119
	v_max_f32_e32 v4, v118, v118
	v_max_f32_e32 v3, v4, v3
	v_max3_f32 v0, v0, v2, v3
	v_max_f32_e32 v2, v25, v25
	v_max_f32_e32 v3, v24, v24
	v_max_f32_e32 v2, v3, v2
	v_max_f32_e32 v3, v23, v23
	v_max_f32_e32 v4, v22, v22
	v_max_f32_e32 v3, v4, v3
	v_max3_f32 v0, v0, v2, v3
	v_max_f32_e32 v2, v21, v21
	v_max_f32_e32 v3, v20, v20
	v_max_f32_e32 v2, v3, v2
	v_max_f32_e32 v3, v19, v19
	v_max_f32_e32 v4, v18, v18
	v_max_f32_e32 v3, v4, v3
	v_max3_f32 v0, v0, v2, v3
	v_max_f32_e32 v2, v13, v13
	v_max_f32_e32 v3, v12, v12
	v_max_f32_e32 v2, v3, v2
	v_max_f32_e32 v3, v7, v7
	v_max_f32_e32 v4, v6, v6
	s_or_b64 vcc, vcc, s[42:43]
	v_max_f32_e32 v3, v4, v3
	v_cndmask_b32_e32 v11, v33, v219, vcc
	v_max3_f32 v0, v0, v2, v3
	v_max_f32_e32 v2, v9, v9
	v_max_f32_e32 v3, v8, v8
	v_max_f32_e32 v2, v3, v2
	v_max_f32_e32 v3, v11, v11
	v_max_f32_e32 v4, v10, v10
	v_max_f32_e32 v3, v4, v3
	v_max3_f32 v14, v0, v2, v3
	v_readlane_b32 s42, v255, 25
	v_lshlrev_b32_e32 v0, 9, v158
	v_readlane_b32 s43, v255, 26
	s_add_u32 s42, s96, s42
	v_and_b32_e32 v0, 0x1000, v0
	v_lshlrev_b32_e32 v2, 6, v116
	s_addc_u32 s43, s97, s43
	v_add3_u32 v0, s33, v0, v2
	v_and_b32_e32 v2, 56, v117
	v_add_u32_e32 v16, v0, v2
	v_lshl_add_u64 v[2:3], s[42:43], 0, v[114:115]
	v_lshlrev_b32_e32 v0, 2, v135
	s_movk_i32 s42, 0xf000
	v_mov_b32_e32 v15, v14
	v_lshl_add_u64 v[4:5], v[2:3], 0, v[0:1]
	s_mov_b32 s43, -1
	v_permlane32_swap_b32_e32 v14, v15
	v_lshl_add_u64 v[2:3], v[4:5], 0, s[42:43]
	s_waitcnt vmcnt(15)
	v_cvt_pk_bf16_f32 v26, v90, v91
	v_cvt_pk_bf16_f32 v27, v92, v93
	ds_write_b64 v16, v[26:27] offset:8192
	s_and_saveexec_b64 s[42:43], s[8:9]
	s_cbranch_execz .LBB0_1275
	global_store_dwordx4 v[2:3], v[90:93], off nt
.LBB0_1275:
	s_or_b64 exec, exec, s[42:43]
	s_waitcnt vmcnt(14)
	v_cvt_pk_bf16_f32 v26, v86, v87
	v_cvt_pk_bf16_f32 v27, v88, v89
	ds_write_b64 v16, v[26:27] offset:8448
	s_and_saveexec_b64 s[8:9], s[10:11]
	s_cbranch_execz .LBB0_1277
	global_store_dwordx4 v[4:5], v[86:89], off nt
.LBB0_1277:
	s_or_b64 exec, exec, s[8:9]
	s_waitcnt vmcnt(13)
	v_cvt_pk_bf16_f32 v4, v58, v59
	v_cvt_pk_bf16_f32 v5, v60, v61
	ds_write_b64 v16, v[4:5] offset:8704
	s_and_saveexec_b64 s[8:9], s[12:13]
	s_cbranch_execz .LBB0_1279
	v_add_co_u32_e32 v4, vcc, 0x2000, v2
	s_nop 1
	v_addc_co_u32_e32 v5, vcc, 0, v3, vcc
	global_store_dwordx4 v[4:5], v[58:61], off nt
; #define LAS __attribute__((address_space(3)))
; __device__ __forceinline__ unsigned cvt_pk_bf16(float lo, float hi) { unsigned r; asm volatile("v_cvt_pk_bf16_f32 %0, %1, %2" : "=v"(r) : "v"(lo), "v"(hi)); return r; }
; __device__ __forceinline__ void f32_v_commit(const F32Half& T, LAS unsigned char* vb, int lane, float* vcopy, int skip, int h) {
;     const int pc = lane & 15, rl = lane >> 4;
;     LAS unsigned char* vd = vb + (pc >> 3) * 4096 + rl * 64 + (pc & 7) * 8; float* vc = vcopy + (size_t)rl * 256 + pc * 4;
; #pragma unroll
;     for (int i = 0; i < 8; ++i) { const int ri = 4 * (8 * h + i); u32x2 w; w.x = cvt_pk_bf16(T.x[i][0], T.x[i][1]); w.y = cvt_pk_bf16(T.x[i][2], T.x[i][3]);
;         *(LAS u32x2*)(vd + ri * 64) = w;
;         if (vcopy && ri + rl >= skip) *(f32x4*)(vc + (size_t)ri * 256) = T.x[i]; }
; }
.LBB0_1279:
	s_or_b64 exec, exec, s[8:9]
	s_waitcnt vmcnt(12)
	v_cvt_pk_bf16_f32 v4, v50, v51
	v_cvt_pk_bf16_f32 v5, v52, v53
	ds_write_b64 v16, v[4:5] offset:8960
	s_and_saveexec_b64 s[8:9], s[14:15]
	s_cbranch_execz .LBB0_1281
	v_add_co_u32_e32 v4, vcc, 0x3000, v2
	s_nop 1
	v_addc_co_u32_e32 v5, vcc, 0, v3, vcc
	global_store_dwordx4 v[4:5], v[50:53], off nt
.LBB0_1281:
	s_or_b64 exec, exec, s[8:9]
	s_waitcnt vmcnt(11)
	v_cvt_pk_bf16_f32 v4, v46, v47
	v_cvt_pk_bf16_f32 v5, v48, v49
	ds_write_b64 v16, v[4:5] offset:9216
	s_and_saveexec_b64 s[8:9], s[16:17]
	s_cbranch_execz .LBB0_1283
	v_add_co_u32_e32 v4, vcc, 0x4000, v2
	s_nop 1
	v_addc_co_u32_e32 v5, vcc, 0, v3, vcc
	global_store_dwordx4 v[4:5], v[46:49], off nt
.LBB0_1283:
	s_or_b64 exec, exec, s[8:9]
	s_waitcnt vmcnt(10)
	v_cvt_pk_bf16_f32 v4, v42, v43
	v_cvt_pk_bf16_f32 v5, v44, v45
	ds_write_b64 v16, v[4:5] offset:9472
	s_and_saveexec_b64 s[8:9], s[18:19]
	s_cbranch_execz .LBB0_1285
	v_add_co_u32_e32 v4, vcc, 0x5000, v2
	s_nop 1
	v_addc_co_u32_e32 v5, vcc, 0, v3, vcc
	global_store_dwordx4 v[4:5], v[42:45], off nt
.LBB0_1285:
	s_or_b64 exec, exec, s[8:9]
	s_waitcnt vmcnt(9)
	v_cvt_pk_bf16_f32 v4, v38, v39
	v_cvt_pk_bf16_f32 v5, v40, v41
	ds_write_b64 v16, v[4:5] offset:9728
	s_and_saveexec_b64 s[8:9], s[20:21]
	s_cbranch_execz .LBB0_1287
	v_add_co_u32_e32 v4, vcc, 0x6000, v2
	s_nop 1
	v_addc_co_u32_e32 v5, vcc, 0, v3, vcc
	global_store_dwordx4 v[4:5], v[38:41], off nt
.LBB0_1287:
	s_or_b64 exec, exec, s[8:9]
	s_waitcnt vmcnt(8)
	v_cvt_pk_bf16_f32 v4, v34, v35
	v_cvt_pk_bf16_f32 v5, v36, v37
	ds_write_b64 v16, v[4:5] offset:9984
	s_and_saveexec_b64 s[8:9], s[22:23]
	s_cbranch_execz .LBB0_1289
	v_add_co_u32_e32 v4, vcc, 0x7000, v2
	s_nop 1
	v_addc_co_u32_e32 v5, vcc, 0, v3, vcc
	global_store_dwordx4 v[4:5], v[34:37], off nt
.LBB0_1289:
	s_or_b64 exec, exec, s[8:9]
	s_waitcnt vmcnt(7)
	v_cvt_pk_bf16_f32 v4, v110, v111
	v_cvt_pk_bf16_f32 v5, v112, v113
	ds_write_b64 v16, v[4:5] offset:10240
	s_and_saveexec_b64 s[8:9], s[24:25]
	s_cbranch_execz .LBB0_1291
	v_add_co_u32_e32 v4, vcc, 0x8000, v2
	s_nop 1
	v_addc_co_u32_e32 v5, vcc, 0, v3, vcc
	global_store_dwordx4 v[4:5], v[110:113], off nt
.LBB0_1291:
	s_or_b64 exec, exec, s[8:9]
	s_waitcnt vmcnt(6)
	v_cvt_pk_bf16_f32 v4, v106, v107
	v_cvt_pk_bf16_f32 v5, v108, v109
	ds_write_b64 v16, v[4:5] offset:10496
	s_and_saveexec_b64 s[8:9], s[26:27]
	s_cbranch_execz .LBB0_1293
	v_add_co_u32_e32 v4, vcc, 0x9000, v2
	s_nop 1
	v_addc_co_u32_e32 v5, vcc, 0, v3, vcc
	global_store_dwordx4 v[4:5], v[106:109], off nt
.LBB0_1293:
	s_or_b64 exec, exec, s[8:9]
	s_waitcnt vmcnt(5)
	v_cvt_pk_bf16_f32 v4, v102, v103
	v_cvt_pk_bf16_f32 v5, v104, v105
	ds_write_b64 v16, v[4:5] offset:10752
	s_and_saveexec_b64 s[8:9], s[28:29]
	s_cbranch_execz .LBB0_1295
	v_add_co_u32_e32 v4, vcc, 0xa000, v2
	s_nop 1
	v_addc_co_u32_e32 v5, vcc, 0, v3, vcc
	global_store_dwordx4 v[4:5], v[102:105], off nt
.LBB0_1295:
	s_or_b64 exec, exec, s[8:9]
	s_waitcnt vmcnt(4)
	v_cvt_pk_bf16_f32 v4, v98, v99
	v_cvt_pk_bf16_f32 v5, v100, v101
	ds_write_b64 v16, v[4:5] offset:11008
	s_and_saveexec_b64 s[8:9], s[30:31]
	s_cbranch_execz .LBB0_1297
	v_add_co_u32_e32 v4, vcc, 0xb000, v2
	s_nop 1
	v_addc_co_u32_e32 v5, vcc, 0, v3, vcc
	global_store_dwordx4 v[4:5], v[98:101], off nt
.LBB0_1297:
	s_or_b64 exec, exec, s[8:9]
	s_waitcnt vmcnt(3)
	v_cvt_pk_bf16_f32 v4, v94, v95
	v_cvt_pk_bf16_f32 v5, v96, v97
	ds_write_b64 v16, v[4:5] offset:11264
	s_and_saveexec_b64 s[8:9], s[34:35]
	s_cbranch_execz .LBB0_1299
	v_add_co_u32_e32 v4, vcc, 0xc000, v2
	s_nop 1
	v_addc_co_u32_e32 v5, vcc, 0, v3, vcc
	global_store_dwordx4 v[4:5], v[94:97], off nt
.LBB0_1299:
	s_or_b64 exec, exec, s[8:9]
	s_waitcnt vmcnt(2)
	v_cvt_pk_bf16_f32 v4, v82, v83
	v_cvt_pk_bf16_f32 v5, v84, v85
	ds_write_b64 v16, v[4:5] offset:11520
	s_and_saveexec_b64 s[8:9], s[36:37]
	s_cbranch_execz .LBB0_1301
	v_add_co_u32_e32 v4, vcc, 0xd000, v2
	s_nop 1
	v_addc_co_u32_e32 v5, vcc, 0, v3, vcc
	global_store_dwordx4 v[4:5], v[82:85], off nt
.LBB0_1301:
	s_or_b64 exec, exec, s[8:9]
	s_waitcnt vmcnt(1)
	v_cvt_pk_bf16_f32 v4, v62, v63
	v_cvt_pk_bf16_f32 v5, v64, v65
	ds_write_b64 v16, v[4:5] offset:11776
	s_and_saveexec_b64 s[8:9], s[38:39]
	s_cbranch_execz .LBB0_1303
	v_add_co_u32_e32 v4, vcc, 0xe000, v2
	s_nop 1
	v_addc_co_u32_e32 v5, vcc, 0, v3, vcc
	global_store_dwordx4 v[4:5], v[62:65], off nt
.LBB0_1303:
	s_or_b64 exec, exec, s[8:9]
	s_waitcnt vmcnt(0)
	v_cvt_pk_bf16_f32 v4, v54, v55
	v_cvt_pk_bf16_f32 v5, v56, v57
	ds_write_b64 v16, v[4:5] offset:12032
	s_and_saveexec_b64 s[8:9], s[40:41]
	s_cbranch_execz .LBB0_1305
	v_add_co_u32_e32 v2, vcc, 0xf000, v2
	s_nop 1
	v_addc_co_u32_e32 v3, vcc, 0, v3, vcc
	global_store_dwordx4 v[2:3], v[54:57], off nt

; #define LAS __attribute__((address_space(3)))
; __device__ __forceinline__ unsigned cvt_pk_bf16(float lo, float hi) { unsigned r; asm volatile("v_cvt_pk_bf16_f32 %0, %1, %2" : "=v"(r) : "v"(lo), "v"(hi)); return r; }
; #define LDS_WAIT() asm volatile("s_waitcnt lgkmcnt(0)" ::: "memory")
; __device__ __forceinline__ void f32_k_issue(F32Tile& T, const float* kp, int lane) {
;     const float* kl = kp + (size_t)(lane >> 4) * 256 + (lane & 15) * 4;
; #pragma unroll
;     for (int i = 0; i < 16; ++i) T.x[i] = *(const f32x4*)(kl + (size_t)(4 * i) * 256);
; }
; template <int H> __device__ __forceinline__ void f32_k_commit(const F32Tile& T, LAS unsigned char* kb, int lane, float* kcopy, int skip) {
;     const int pc = lane & 15, rl = lane >> 4, c = pc >> 1;
;     float* kc = kcopy + (size_t)rl * 256 + pc * 4;
;     const unsigned keo = (unsigned)(c * 1024 + (pc & 1) * 8 + ((rl + c) & 7) * 16);
;     if (H == 0) LDS_WAIT();
; #pragma unroll
;     for (int i = 8 * H; i < 8 * H + 8; ++i) { u32x2 w; w.x = cvt_pk_bf16(T.x[i][0], T.x[i][1]); w.y = cvt_pk_bf16(T.x[i][2], T.x[i][3]);
;         *(LAS u32x2*)(kb + ((i & 1) ? (keo ^ 64u) : keo) + 128 * (i >> 1)) = w;
;         if (kcopy && 4 * i + rl >= skip) *(f32x4*)(kc + (size_t)(4 * i) * 256) = T.x[i]; }
;     if (H == 1) LDS_WAIT();
; }
; __device__ __forceinline__ void attn_decode_unit(const Params& P, const Ctx& C, int sg) {
;     ...
;     __syncthreads();
;     float m_s = -1e30f, l_s = 0.f; f32x16 os0 = F16Z, os1 = F16Z;
;     if (wave == 0) {
;         F32_TILE_STEP(sk, sv, ck - 4 * 256, cv - 4 * 256, 4, 0, qi + 1, 512 + qi, true, m_w, l_w, ow0, ow1);
.LBB0_1307:
	v_lshlrev_b32_e32 v231, 6, v227
	s_lshl_b32 s64, s53, 6
	s_and_b64 vcc, exec, s[6:7]
	s_waitcnt lgkmcnt(0)
	s_barrier
	s_cbranch_vccnz .LBB0_1373
	v_ashrrev_i32_e32 v152, 4, v165
	v_ashrrev_i32_e32 v153, 31, v152
	v_lshlrev_b64 v[82:83], 10, v[152:153]
	v_lshl_add_u64 v[34:35], s[56:57], 0, v[82:83]
	v_mov_b32_e32 v123, v1
	v_lshl_add_u64 v[34:35], v[34:35], 0, v[122:123]
	v_add_co_u32_e32 v36, vcc, 0x1000, v34
	v_lshl_add_u64 v[86:87], s[54:55], 0, v[82:83]
	s_nop 0
	v_addc_co_u32_e32 v37, vcc, 0, v35, vcc
	global_load_dwordx4 v[146:149], v[34:35], off nt
	global_load_dwordx4 v[142:145], v[36:37], off nt
	v_add_co_u32_e32 v36, vcc, 0x2000, v34
	v_lshl_add_u64 v[154:155], v[86:87], 0, v[122:123]
	s_nop 0
	v_addc_co_u32_e32 v37, vcc, 0, v35, vcc
	v_add_co_u32_e32 v38, vcc, 0x3000, v34
	s_movk_i32 s6, 0x2000
	s_nop 0
	v_addc_co_u32_e32 v39, vcc, 0, v35, vcc
	global_load_dwordx4 v[138:141], v[36:37], off nt
	global_load_dwordx4 v[130:133], v[38:39], off nt
	v_add_co_u32_e32 v36, vcc, 0x4000, v34
	v_lshl_add_u64 v[156:157], s[2:3], 0, v[82:83]
	s_nop 0
	v_addc_co_u32_e32 v37, vcc, 0, v35, vcc
	v_add_co_u32_e32 v38, vcc, 0x5000, v34
	v_mov_b32_e32 v151, v1
	s_nop 0
	v_addc_co_u32_e32 v39, vcc, 0, v35, vcc
	global_load_dwordx4 v[126:129], v[36:37], off nt
	global_load_dwordx4 v[118:121], v[38:39], off nt
	v_add_co_u32_e32 v36, vcc, 0x6000, v34
	s_movk_i32 s2, 0xf000
	s_nop 0
	v_addc_co_u32_e32 v37, vcc, 0, v35, vcc
	v_add_co_u32_e32 v38, vcc, 0x7000, v34
	v_lshlrev_b32_e32 v160, 3, v165
	s_nop 0
	v_addc_co_u32_e32 v39, vcc, 0, v35, vcc
	global_load_dwordx4 v[114:117], v[36:37], off nt
	global_load_dwordx4 v[106:109], v[38:39], off nt
	v_add_co_u32_e32 v36, vcc, 0x8000, v34
	v_lshl_add_u64 v[156:157], v[156:157], 0, v[150:151]
	s_nop 0
	v_addc_co_u32_e32 v37, vcc, 0, v35, vcc
	v_add_co_u32_e32 v38, vcc, 0x9000, v34
	s_mov_b32 s3, -1
	s_nop 0
	v_addc_co_u32_e32 v39, vcc, 0, v35, vcc
	global_load_dwordx4 v[62:65], v[36:37], off nt
	global_load_dwordx4 v[58:61], v[38:39], off nt
	v_add_co_u32_e32 v36, vcc, 0xa000, v34
	v_and_b32_e32 v0, 8, v160
	s_nop 0
	v_addc_co_u32_e32 v37, vcc, 0, v35, vcc
	v_add_co_u32_e32 v38, vcc, 0xb000, v34
	v_lshl_add_u64 v[150:151], v[156:157], 0, s[2:3]
	s_nop 0
	v_addc_co_u32_e32 v39, vcc, 0, v35, vcc
	global_load_dwordx4 v[54:57], v[36:37], off nt
	global_load_dwordx4 v[50:53], v[38:39], off nt
	v_add_co_u32_e32 v36, vcc, 0xc000, v34
	v_lshl_or_b32 v0, v159, 10, v0
	s_nop 0
	v_addc_co_u32_e32 v37, vcc, 0, v35, vcc
	v_add_co_u32_e32 v38, vcc, 0xd000, v34
	v_add_lshl_u32 v153, v159, v152, 4
	s_nop 0
	v_addc_co_u32_e32 v39, vcc, 0, v35, vcc
	global_load_dwordx4 v[46:49], v[36:37], off nt
	global_load_dwordx4 v[42:45], v[38:39], off nt
	v_add_co_u32_e32 v36, vcc, 0xe000, v34
	s_movk_i32 s2, 0x70
	s_nop 0
	v_addc_co_u32_e32 v37, vcc, 0, v35, vcc
	v_add_co_u32_e32 v34, vcc, 0xf000, v34
	v_and_or_b32 v0, v153, s2, v0
	s_nop 0
	v_addc_co_u32_e32 v35, vcc, 0, v35, vcc
	v_add_co_u32_e32 v86, vcc, s6, v154
	s_movk_i32 s6, 0x4000
	s_nop 0
	v_addc_co_u32_e32 v87, vcc, 0, v155, vcc
	v_add_co_u32_e32 v88, vcc, s6, v154
	s_movk_i32 s6, 0x6000
	s_nop 0
	v_addc_co_u32_e32 v89, vcc, 0, v155, vcc
	v_add_co_u32_e32 v90, vcc, s6, v154
	s_movk_i32 s6, 0x7000
	s_nop 0
	v_addc_co_u32_e32 v91, vcc, 0, v155, vcc
	global_load_dwordx4 v[38:41], v[36:37], off nt
	s_nop 0
	global_load_dwordx4 v[34:37], v[34:35], off nt
	v_add_u32_e32 v153, s33, v0
	global_load_dwordx4 v[122:125], v[154:155], off nt
	global_load_dwordx4 v[110:113], v[86:87], off nt
	global_load_dwordx4 v[102:105], v[88:89], off offset:-4096 nt
	global_load_dwordx4 v[98:101], v[88:89], off nt
	global_load_dwordx4 v[94:97], v[90:91], off offset:-4096 nt
	s_nop 0
	global_load_dwordx4 v[90:93], v[90:91], off nt
	v_add_co_u32_e32 v88, vcc, s6, v154
	v_cmp_lt_i32_e64 s[6:7], 3, v152
	s_nop 0
	v_addc_co_u32_e32 v89, vcc, 0, v155, vcc
	global_load_dwordx4 v[134:137], v[86:87], off offset:-4096 nt
	s_nop 0
	global_load_dwordx4 v[86:89], v[88:89], off nt
	s_waitcnt lgkmcnt(0)
	s_waitcnt vmcnt(23)
	v_cvt_pk_bf16_f32 v168, v146, v147
	v_cvt_pk_bf16_f32 v169, v148, v149
	ds_write_b64 v153, v[168:169]
	s_and_saveexec_b64 s[2:3], s[6:7]
	s_cbranch_execz .LBB0_1310
	global_store_dwordx4 v[150:151], v[146:149], off nt
.LBB0_1310:
	s_or_b64 exec, exec, s[2:3]
	v_xor_b32_e32 v0, 64, v0
	v_add_u32_e32 v0, s33, v0
	v_cmp_lt_i32_e64 s[8:9], -1, v152
	s_waitcnt vmcnt(22)
	v_cvt_pk_bf16_f32 v146, v142, v143
	v_cvt_pk_bf16_f32 v147, v144, v145
	ds_write_b64 v0, v[146:147]
	s_and_saveexec_b64 s[2:3], s[8:9]
	s_cbranch_execz .LBB0_1312
	global_store_dwordx4 v[156:157], v[142:145], off nt
.LBB0_1312:
	s_or_b64 exec, exec, s[2:3]
	v_cmp_lt_i32_e64 s[10:11], -5, v152
	s_waitcnt vmcnt(21)
	v_cvt_pk_bf16_f32 v142, v138, v139
	v_cvt_pk_bf16_f32 v143, v140, v141
	ds_write_b64 v153, v[142:143] offset:128
	s_and_saveexec_b64 s[2:3], s[10:11]
	s_cbranch_execz .LBB0_1314
	v_add_co_u32_e32 v142, vcc, 0x2000, v150
	s_nop 1
	v_addc_co_u32_e32 v143, vcc, 0, v151, vcc
	global_store_dwordx4 v[142:143], v[138:141], off nt
.LBB0_1314:
	s_or_b64 exec, exec, s[2:3]
	v_cmp_lt_i32_e64 s[12:13], -9, v152
	s_waitcnt vmcnt(20)
	v_cvt_pk_bf16_f32 v138, v130, v131
	v_cvt_pk_bf16_f32 v139, v132, v133
	ds_write_b64 v0, v[138:139] offset:128
	s_and_saveexec_b64 s[2:3], s[12:13]
	s_cbranch_execz .LBB0_1316
	v_add_co_u32_e32 v138, vcc, 0x3000, v150
	s_nop 1
	v_addc_co_u32_e32 v139, vcc, 0, v151, vcc
	global_store_dwordx4 v[138:139], v[130:133], off nt
; #define LAS __attribute__((address_space(3)))
; __device__ __forceinline__ unsigned cvt_pk_bf16(float lo, float hi) { unsigned r; asm volatile("v_cvt_pk_bf16_f32 %0, %1, %2" : "=v"(r) : "v"(lo), "v"(hi)); return r; }
; #define LDS_WAIT() asm volatile("s_waitcnt lgkmcnt(0)" ::: "memory")
; template <int H> __device__ __forceinline__ void f32_k_commit(const F32Tile& T, LAS unsigned char* kb, int lane, float* kcopy, int skip) {
;     const int pc = lane & 15, rl = lane >> 4, c = pc >> 1;
;     float* kc = kcopy + (size_t)rl * 256 + pc * 4;
;     const unsigned keo = (unsigned)(c * 1024 + (pc & 1) * 8 + ((rl + c) & 7) * 16);
;     if (H == 0) LDS_WAIT();
; #pragma unroll
;     for (int i = 8 * H; i < 8 * H + 8; ++i) { u32x2 w; w.x = cvt_pk_bf16(T.x[i][0], T.x[i][1]); w.y = cvt_pk_bf16(T.x[i][2], T.x[i][3]);
;         *(LAS u32x2*)(kb + ((i & 1) ? (keo ^ 64u) : keo) + 128 * (i >> 1)) = w;
;         if (kcopy && 4 * i + rl >= skip) *(f32x4*)(kc + (size_t)(4 * i) * 256) = T.x[i]; }
;     if (H == 1) LDS_WAIT();
; }
; __device__ __forceinline__ void f32_v_issue(F32Half& T, const float* vp, int lane, int h) {
;     const float* vl = vp + (size_t)(lane >> 4) * 256 + (lane & 15) * 4;
; #pragma unroll
;     for (int i = 0; i < 8; ++i) T.x[i] = *(const f32x4*)(vl + (size_t)(4 * (8 * h + i)) * 256);
; }
.LBB0_1316:
	s_or_b64 exec, exec, s[2:3]
	v_cmp_lt_i32_e64 s[14:15], -13, v152
	s_waitcnt vmcnt(19)
	v_cvt_pk_bf16_f32 v130, v126, v127
	v_cvt_pk_bf16_f32 v131, v128, v129
	ds_write_b64 v153, v[130:131] offset:256
	s_and_saveexec_b64 s[2:3], s[14:15]
	s_cbranch_execz .LBB0_1318
	v_add_co_u32_e32 v130, vcc, 0x4000, v150
	s_nop 1
	v_addc_co_u32_e32 v131, vcc, 0, v151, vcc
	global_store_dwordx4 v[130:131], v[126:129], off nt
.LBB0_1318:
	s_or_b64 exec, exec, s[2:3]
	s_movk_i32 s2, 0xffef
	v_cmp_lt_i32_e64 s[16:17], s2, v152
	s_waitcnt vmcnt(18)
	v_cvt_pk_bf16_f32 v126, v118, v119
	v_cvt_pk_bf16_f32 v127, v120, v121
	ds_write_b64 v0, v[126:127] offset:256
	s_and_saveexec_b64 s[2:3], s[16:17]
	s_cbranch_execz .LBB0_1320
	v_add_co_u32_e32 v126, vcc, 0x5000, v150
	s_nop 1
	v_addc_co_u32_e32 v127, vcc, 0, v151, vcc
	global_store_dwordx4 v[126:127], v[118:121], off nt
.LBB0_1320:
	s_or_b64 exec, exec, s[2:3]
	s_movk_i32 s2, 0xffeb
	v_cmp_lt_i32_e64 s[18:19], s2, v152
	s_waitcnt vmcnt(17)
	v_cvt_pk_bf16_f32 v118, v114, v115
	v_cvt_pk_bf16_f32 v119, v116, v117
	ds_write_b64 v153, v[118:119] offset:384
	s_and_saveexec_b64 s[2:3], s[18:19]
	s_cbranch_execz .LBB0_1322
	v_add_co_u32_e32 v118, vcc, 0x6000, v150
	s_nop 1
	v_addc_co_u32_e32 v119, vcc, 0, v151, vcc
	global_store_dwordx4 v[118:119], v[114:117], off nt
.LBB0_1322:
	s_or_b64 exec, exec, s[2:3]
	s_movk_i32 s2, 0xffe7
	v_cmp_lt_i32_e64 s[20:21], s2, v152
	s_waitcnt vmcnt(16)
	v_cvt_pk_bf16_f32 v114, v106, v107
	v_cvt_pk_bf16_f32 v115, v108, v109
	ds_write_b64 v0, v[114:115] offset:384
	s_and_saveexec_b64 s[2:3], s[20:21]
	s_cbranch_execz .LBB0_1324
	v_add_co_u32_e32 v114, vcc, 0x7000, v150
	s_nop 1
	v_addc_co_u32_e32 v115, vcc, 0, v151, vcc
	global_store_dwordx4 v[114:115], v[106:109], off nt
.LBB0_1324:
	s_or_b64 exec, exec, s[2:3]
	s_nop 0
	v_add_co_u32_e32 v106, vcc, 0x8000, v154
	s_movk_i32 s2, 0xffe3
	s_nop 0
	v_addc_co_u32_e32 v107, vcc, 0, v155, vcc
	v_add_co_u32_e32 v108, vcc, 0x9000, v154
	v_cmp_lt_i32_e64 s[22:23], s2, v152
	s_nop 0
	v_addc_co_u32_e32 v109, vcc, 0, v155, vcc
	global_load_dwordx4 v[146:149], v[106:107], off nt
	global_load_dwordx4 v[142:145], v[108:109], off nt
	v_add_co_u32_e32 v106, vcc, 0xa000, v154
	s_nop 1
	v_addc_co_u32_e32 v107, vcc, 0, v155, vcc
	v_add_co_u32_e32 v108, vcc, 0xb000, v154
	s_nop 1
	v_addc_co_u32_e32 v109, vcc, 0, v155, vcc
	global_load_dwordx4 v[138:141], v[106:107], off nt
	global_load_dwordx4 v[130:133], v[108:109], off nt
	v_add_co_u32_e32 v106, vcc, 0xc000, v154
	s_nop 1
	v_addc_co_u32_e32 v107, vcc, 0, v155, vcc
	v_add_co_u32_e32 v108, vcc, 0xd000, v154
	s_nop 1
	v_addc_co_u32_e32 v109, vcc, 0, v155, vcc
	global_load_dwordx4 v[126:129], v[106:107], off nt
	global_load_dwordx4 v[118:121], v[108:109], off nt
	v_add_co_u32_e32 v106, vcc, 0xe000, v154
	s_nop 1
	v_addc_co_u32_e32 v107, vcc, 0, v155, vcc
	v_add_co_u32_e32 v108, vcc, 0xf000, v154
	s_nop 1
	v_addc_co_u32_e32 v109, vcc, 0, v155, vcc
	global_load_dwordx4 v[114:117], v[106:107], off nt
	s_nop 0
	global_load_dwordx4 v[106:109], v[108:109], off nt
	s_waitcnt vmcnt(23)
	v_cvt_pk_bf16_f32 v154, v62, v63
	v_cvt_pk_bf16_f32 v155, v64, v65
	ds_write_b64 v153, v[154:155] offset:512
	s_and_saveexec_b64 s[2:3], s[22:23]
	s_cbranch_execz .LBB0_1326
	v_add_co_u32_e32 v154, vcc, 0x8000, v150
	s_nop 1
	v_addc_co_u32_e32 v155, vcc, 0, v151, vcc
	global_store_dwordx4 v[154:155], v[62:65], off nt
.LBB0_1326:
	s_or_b64 exec, exec, s[2:3]
	s_movk_i32 s2, 0xffdf
	v_cmp_lt_i32_e64 s[24:25], s2, v152
	s_waitcnt vmcnt(22)
	v_cvt_pk_bf16_f32 v62, v58, v59
	v_cvt_pk_bf16_f32 v63, v60, v61
	ds_write_b64 v0, v[62:63] offset:512
	s_and_saveexec_b64 s[2:3], s[24:25]
	s_cbranch_execz .LBB0_1328
	v_add_co_u32_e32 v62, vcc, 0x9000, v150
	s_nop 1
	v_addc_co_u32_e32 v63, vcc, 0, v151, vcc
	global_store_dwordx4 v[62:63], v[58:61], off nt
.LBB0_1328:
	s_or_b64 exec, exec, s[2:3]
	s_movk_i32 s2, 0xffdb
	v_cmp_lt_i32_e64 s[26:27], s2, v152
	s_waitcnt vmcnt(21)
	v_cvt_pk_bf16_f32 v58, v54, v55
	v_cvt_pk_bf16_f32 v59, v56, v57
	ds_write_b64 v153, v[58:59] offset:640
	s_and_saveexec_b64 s[2:3], s[26:27]
	s_cbranch_execz .LBB0_1330
	v_add_co_u32_e32 v58, vcc, 0xa000, v150
	s_nop 1
	v_addc_co_u32_e32 v59, vcc, 0, v151, vcc
	global_store_dwordx4 v[58:59], v[54:57], off nt
.LBB0_1330:
	s_or_b64 exec, exec, s[2:3]
	s_movk_i32 s2, 0xffd7
	v_cmp_lt_i32_e64 s[28:29], s2, v152
	s_waitcnt vmcnt(20)
	v_cvt_pk_bf16_f32 v54, v50, v51
	v_cvt_pk_bf16_f32 v55, v52, v53
	ds_write_b64 v0, v[54:55] offset:640
	s_and_saveexec_b64 s[2:3], s[28:29]
	s_cbranch_execz .LBB0_1332
	v_add_co_u32_e32 v54, vcc, 0xb000, v150
	s_nop 1
	v_addc_co_u32_e32 v55, vcc, 0, v151, vcc
	global_store_dwordx4 v[54:55], v[50:53], off nt
.LBB0_1332:
	s_or_b64 exec, exec, s[2:3]
	s_movk_i32 s2, 0xffd3
	v_cmp_lt_i32_e64 s[30:31], s2, v152
	s_waitcnt vmcnt(19)
	v_cvt_pk_bf16_f32 v50, v46, v47
	v_cvt_pk_bf16_f32 v51, v48, v49
	ds_write_b64 v153, v[50:51] offset:768
	s_and_saveexec_b64 s[2:3], s[30:31]
	s_cbranch_execz .LBB0_1334
	v_add_co_u32_e32 v50, vcc, 0xc000, v150
	s_nop 1
	v_addc_co_u32_e32 v51, vcc, 0, v151, vcc
	global_store_dwordx4 v[50:51], v[46:49], off nt
.LBB0_1334:
	s_or_b64 exec, exec, s[2:3]
	s_movk_i32 s2, 0xffcf
	v_cmp_lt_i32_e64 s[34:35], s2, v152
	s_waitcnt vmcnt(18)
	v_cvt_pk_bf16_f32 v46, v42, v43
	v_cvt_pk_bf16_f32 v47, v44, v45
	ds_write_b64 v0, v[46:47] offset:768
	s_and_saveexec_b64 s[2:3], s[34:35]
	s_cbranch_execz .LBB0_1336
	v_add_co_u32_e32 v46, vcc, 0xd000, v150
	s_nop 1
	v_addc_co_u32_e32 v47, vcc, 0, v151, vcc
	global_store_dwordx4 v[46:47], v[42:45], off nt
; #define LAS __attribute__((address_space(3)))
; __device__ __forceinline__ unsigned cvt_pk_bf16(float lo, float hi) { unsigned r; asm volatile("v_cvt_pk_bf16_f32 %0, %1, %2" : "=v"(r) : "v"(lo), "v"(hi)); return r; }
; __device__ __forceinline__ int crow(int r, int hi) { return (r & 3) + 8 * (r >> 2) + 4 * hi; }
; #define LDS_WAIT() asm volatile("s_waitcnt lgkmcnt(0)" ::: "memory")
; __device__ __forceinline__ void qk_tile_sw(const LAS unsigned char* kb, const bf16x8 (&qr)[4], f32x16& s0, f32x16& s1, int r32, int hi) {
;     f32x16 a = {0.f, 0.f, 0.f, 0.f, 0.f, 0.f, 0.f, 0.f, 0.f, 0.f, 0.f, 0.f, 0.f, 0.f, 0.f, 0.f}, b = a;
;     const LAS unsigned char* kp = kb + hi * 1024 + (r32 & ~7) * 16;
; #pragma unroll
;     for (int d0 = 0; d0 < 4; ++d0) { const int lo = (r32 + 2 * d0 + hi) & 7;
;         const bf16x8 k0 = *(const LAS bf16x8*)(kp + d0 * 2048 + lo * 16), k1 = *(const LAS bf16x8*)(kp + d0 * 2048 + lo * 16 + 512);
;         a = MFMA32(k0, qr[d0], a); b = MFMA32(k1, qr[d0], b);
;     }
;     s0 = a; s1 = b;
; }
; __device__ __forceinline__ void qk_tile(const LAS unsigned char* kb, const bf16x8 (&qr)[4], f32x16& s0, f32x16& s1, int r32, int hi) {
;     const LAS unsigned char* kp = kb + hi * 1024 + r32 * 16;
;     f32x16 a = F16Z, b = F16Z;
; #pragma unroll
;     for (int d0 = 0; d0 < 4; ++d0) {
;         const bf16x8 k0 = *(const LAS bf16x8*)(kp + d0 * 2048), k1 = *(const LAS bf16x8*)(kp + d0 * 2048 + 512);
;         a = MFMA32(k0, qr[d0], a); b = MFMA32(k1, qr[d0], b);
;     }
;     s0 = a; s1 = b;
; }
; __device__ __forceinline__ void mask_tile(f32x16& s0, f32x16& s1, int key0, int klo, int khi, bool en, int hi) {
; #pragma unroll
;     for (int r = 0; r < 16; ++r) { const int k = key0 + crow(r, hi);
;         if (!(en && k >= klo && k <= khi)) s0[r] = NEG_INF;
;         if (!(en && k + 32 >= klo && k + 32 <= khi)) s1[r] = NEG_INF; }
; }
; template <int H> __device__ __forceinline__ void f32_k_commit(const F32Tile& T, LAS unsigned char* kb, int lane, float* kcopy, int skip) {
;     ...
;     for (int i = 8 * H; i < 8 * H + 8; ++i) { u32x2 w; w.x = cvt_pk_bf16(T.x[i][0], T.x[i][1]); w.y = cvt_pk_bf16(T.x[i][2], T.x[i][3]);
;         *(LAS u32x2*)(kb + ((i & 1) ? (keo ^ 64u) : keo) + 128 * (i >> 1)) = w;
;         if (kcopy && 4 * i + rl >= skip) *(f32x4*)(kc + (size_t)(4 * i) * 256) = T.x[i]; }
;     if (H == 1) LDS_WAIT();
; }
.LBB0_1336:
	s_or_b64 exec, exec, s[2:3]
	s_movk_i32 s2, 0xffcb
	v_cmp_lt_i32_e64 s[36:37], s2, v152
	s_waitcnt vmcnt(17)
	v_cvt_pk_bf16_f32 v42, v38, v39
	v_cvt_pk_bf16_f32 v43, v40, v41
	ds_write_b64 v153, v[42:43] offset:896
	s_and_saveexec_b64 s[2:3], s[36:37]
	s_cbranch_execz .LBB0_1338
	v_add_co_u32_e32 v42, vcc, 0xe000, v150
	s_nop 1
	v_addc_co_u32_e32 v43, vcc, 0, v151, vcc
	global_store_dwordx4 v[42:43], v[38:41], off nt
.LBB0_1338:
	s_or_b64 exec, exec, s[2:3]
	s_movk_i32 s2, 0xffc7
	v_cmp_lt_i32_e64 s[38:39], s2, v152
	s_waitcnt vmcnt(16)
	v_cvt_pk_bf16_f32 v38, v34, v35
	v_cvt_pk_bf16_f32 v39, v36, v37
	ds_write_b64 v0, v[38:39] offset:896
	s_and_saveexec_b64 s[2:3], s[38:39]
	s_cbranch_execz .LBB0_1340
	v_add_co_u32_e32 v38, vcc, 0xf000, v150
	s_nop 1
	v_addc_co_u32_e32 v39, vcc, 0, v151, vcc
	global_store_dwordx4 v[38:39], v[34:37], off nt
.LBB0_1340:
	s_or_b64 exec, exec, s[2:3]
	v_lshlrev_b32_e32 v153, 4, v228
	v_lshl_add_u32 v151, v166, 10, s33
	v_and_b32_e32 v0, 0x180, v153
	v_add_lshl_u32 v150, v166, v228, 4
	v_add_u32_e32 v0, v151, v0
	v_and_b32_e32 v159, 0x70, v150
	s_waitcnt lgkmcnt(0)
	v_add_u32_e32 v50, v0, v159
	ds_read_b128 v[34:37], v50
	v_add_u32_e32 v54, 32, v150
	v_and_b32_e32 v54, 0x70, v54
	v_add_u32_e32 v161, v0, v54
	ds_read_b128 v[154:157], v161 offset:2048
	s_waitcnt lgkmcnt(1)
	v_mfma_f32_32x32x16_bf16 v[34:49], v[34:37], v[74:77], 0
	ds_read_b128 v[50:53], v50 offset:512
	v_xad_u32 v159, v159, 64, v0
	v_add_u32_e32 v150, 0x60, v150
	v_and_b32_e32 v150, 0x70, v150
	v_add_u32_e32 v0, v0, v150
	v_or_b32_e32 v150, 0x200, v167
	v_cmp_gt_i32_e32 vcc, v164, v167
	s_waitcnt lgkmcnt(1)
	v_mfma_f32_32x32x16_bf16 v[34:49], v[154:157], v[66:69], v[34:49]
	ds_read_b128 v[154:157], v161 offset:2560
	v_cmp_le_i32_e64 s[40:41], v164, v150
	s_and_b64 vcc, vcc, s[40:41]
	v_lshlrev_b32_e32 v178, 2, v158
	s_movk_i32 s2, 0xf000
	s_mov_b32 s3, -1
	ds_read_b128 v[168:171], v0 offset:6656
	s_waitcnt lgkmcnt(2)
	v_mfma_f32_32x32x16_bf16 v[50:65], v[50:53], v[74:77], 0
	s_waitcnt lgkmcnt(1)
	v_mfma_f32_32x32x16_bf16 v[50:65], v[154:157], v[66:69], v[50:65]
	ds_read_b128 v[154:157], v159 offset:4096
	s_waitcnt lgkmcnt(0)
	v_mfma_f32_32x32x16_bf16 v[34:49], v[154:157], v[70:73], v[34:49]
	ds_read_b128 v[154:157], v159 offset:4608
	s_waitcnt lgkmcnt(0)
	v_mfma_f32_32x32x16_bf16 v[50:65], v[154:157], v[70:73], v[50:65]
	ds_read_b128 v[154:157], v0 offset:6144
	v_add_u32_e32 v0, 32, v164
	v_cmp_gt_i32_e64 s[40:41], v0, v150
	s_waitcnt lgkmcnt(0)
	s_waitcnt lgkmcnt(0)
	v_mfma_f32_32x32x16_bf16 v[34:49], v[154:157], v[78:81], v[34:49]
	v_mfma_f32_32x32x16_bf16 v[50:65], v[168:171], v[78:81], v[50:65]
	s_nop 10
	v_cndmask_b32_e32 v173, v219, v34, vcc
	v_cmp_le_i32_e32 vcc, v0, v167
	s_or_b64 vcc, vcc, s[40:41]
	v_cmp_lt_i32_e64 s[40:41], v164, v150
	v_add_u32_e32 v0, 33, v164
	v_cndmask_b32_e32 v177, v50, v219, vcc
	v_cmp_ge_i32_e32 vcc, v164, v167
	s_and_b64 vcc, vcc, s[40:41]
	v_cmp_gt_i32_e64 s[40:41], v0, v150
	v_cndmask_b32_e32 v175, v219, v35, vcc
	v_cmp_le_i32_e32 vcc, v0, v167
	s_or_b64 vcc, vcc, s[40:41]
	v_or_b32_e32 v0, 2, v164
	v_cndmask_b32_e32 v176, v51, v219, vcc
	v_cmp_gt_i32_e32 vcc, v0, v167
	v_cmp_le_i32_e64 s[40:41], v0, v150
	s_and_b64 vcc, vcc, s[40:41]
	v_add_u32_e32 v0, 34, v164
	v_cndmask_b32_e32 v172, v219, v36, vcc
	v_cmp_le_i32_e32 vcc, v0, v167
	v_cmp_gt_i32_e64 s[40:41], v0, v150
	s_or_b64 vcc, vcc, s[40:41]
	v_or_b32_e32 v0, 3, v164
	v_cndmask_b32_e32 v174, v52, v219, vcc
	v_cmp_gt_i32_e32 vcc, v0, v167
	v_cmp_le_i32_e64 s[40:41], v0, v150
	s_and_b64 vcc, vcc, s[40:41]
	v_add_u32_e32 v0, 35, v164
	v_cndmask_b32_e32 v170, v219, v37, vcc
	v_cmp_le_i32_e32 vcc, v0, v167
	v_cmp_gt_i32_e64 s[40:41], v0, v150
	s_or_b64 vcc, vcc, s[40:41]
	v_add_u32_e32 v0, 8, v164
	v_cndmask_b32_e32 v171, v53, v219, vcc
	v_cmp_gt_i32_e32 vcc, v0, v167
	v_cmp_le_i32_e64 s[40:41], v0, v150
	s_and_b64 vcc, vcc, s[40:41]
	v_add_u32_e32 v0, 40, v164
	v_cndmask_b32_e32 v168, v219, v38, vcc
	v_cmp_le_i32_e32 vcc, v0, v167
	v_cmp_gt_i32_e64 s[40:41], v0, v150
	s_or_b64 vcc, vcc, s[40:41]
	v_add_u32_e32 v0, 9, v164
	v_cndmask_b32_e32 v169, v54, v219, vcc
	v_cmp_gt_i32_e32 vcc, v0, v167
	v_cmp_le_i32_e64 s[40:41], v0, v150
	s_and_b64 vcc, vcc, s[40:41]
	v_add_u32_e32 v0, 41, v164
	v_cndmask_b32_e32 v159, v219, v39, vcc
	v_cmp_le_i32_e32 vcc, v0, v167
	v_cmp_gt_i32_e64 s[40:41], v0, v150
	s_or_b64 vcc, vcc, s[40:41]
	v_add_u32_e32 v0, 10, v164
	v_cndmask_b32_e32 v161, v55, v219, vcc
	v_cmp_gt_i32_e32 vcc, v0, v167
	v_cmp_le_i32_e64 s[40:41], v0, v150
	s_and_b64 vcc, vcc, s[40:41]
	v_add_u32_e32 v0, 42, v164
	v_cndmask_b32_e32 v156, v219, v40, vcc
	v_cmp_le_i32_e32 vcc, v0, v167
	v_cmp_gt_i32_e64 s[40:41], v0, v150
	s_or_b64 vcc, vcc, s[40:41]
	v_add_u32_e32 v0, 11, v164
	v_cndmask_b32_e32 v157, v56, v219, vcc
	v_cmp_gt_i32_e32 vcc, v0, v167
	v_cmp_le_i32_e64 s[40:41], v0, v150
	s_and_b64 vcc, vcc, s[40:41]
	v_add_u32_e32 v0, 43, v164
	v_cndmask_b32_e32 v154, v219, v41, vcc
	v_cmp_le_i32_e32 vcc, v0, v167
	v_cmp_gt_i32_e64 s[40:41], v0, v150
	s_or_b64 vcc, vcc, s[40:41]
	v_add_u32_e32 v0, 16, v164
	v_cndmask_b32_e32 v155, v57, v219, vcc
	v_cmp_gt_i32_e32 vcc, v0, v167
	v_cmp_le_i32_e64 s[40:41], v0, v150
	s_and_b64 vcc, vcc, s[40:41]
	v_add_u32_e32 v0, 48, v164
	v_cndmask_b32_e32 v56, v219, v42, vcc
	v_cmp_le_i32_e32 vcc, v0, v167
	v_cmp_gt_i32_e64 s[40:41], v0, v150
	s_or_b64 vcc, vcc, s[40:41]
	v_add_u32_e32 v0, 17, v164
	v_cndmask_b32_e32 v57, v58, v219, vcc
	v_cmp_gt_i32_e32 vcc, v0, v167
	v_cmp_le_i32_e64 s[40:41], v0, v150
	s_and_b64 vcc, vcc, s[40:41]
	v_add_u32_e32 v0, 49, v164
	v_cndmask_b32_e32 v54, v219, v43, vcc
; #define LAS __attribute__((address_space(3)))
; __device__ __forceinline__ unsigned cvt_pk_bf16(float lo, float hi) { unsigned r; asm volatile("v_cvt_pk_bf16_f32 %0, %1, %2" : "=v"(r) : "v"(lo), "v"(hi)); return r; }
; __device__ __forceinline__ int crow(int r, int hi) { return (r & 3) + 8 * (r >> 2) + 4 * hi; }
; __device__ __forceinline__ void mask_tile(f32x16& s0, f32x16& s1, int key0, int klo, int khi, bool en, int hi) {
; #pragma unroll
;     for (int r = 0; r < 16; ++r) { const int k = key0 + crow(r, hi);
;         if (!(en && k >= klo && k <= khi)) s0[r] = NEG_INF;
;         if (!(en && k + 32 >= klo && k + 32 <= khi)) s1[r] = NEG_INF; }
; }
; __device__ __forceinline__ float half_swap_max(float m) { auto rr = __builtin_amdgcn_permlane32_swap(__float_as_uint(m), __float_as_uint(m), false, false); return fmaxf(__uint_as_float(rr[0]), __uint_as_float(rr[1])); }
; __device__ __forceinline__ float half_swap_sum(float m) { auto rr = __builtin_amdgcn_permlane32_swap(__float_as_uint(m), __float_as_uint(m), false, false); return __uint_as_float(rr[0]) + __uint_as_float(rr[1]); }
; __device__ __forceinline__ float tile_max(const f32x16& s0, const f32x16& s1) {
;     float m = fmaxf(s0[0], s1[0]);
; #pragma unroll
;     for (int r = 1; r < 16; ++r) m = fmaxf(m, fmaxf(s0[r], s1[r]));
;     return half_swap_max(m);
; }
; __device__ __forceinline__ void f32_v_commit(const F32Half& T, LAS unsigned char* vb, int lane, float* vcopy, int skip, int h) {
;     const int pc = lane & 15, rl = lane >> 4;
;     LAS unsigned char* vd = vb + (pc >> 3) * 4096 + rl * 64 + (pc & 7) * 8; float* vc = vcopy + (size_t)rl * 256 + pc * 4;
; #pragma unroll
;     for (int i = 0; i < 8; ++i) { const int ri = 4 * (8 * h + i); u32x2 w; w.x = cvt_pk_bf16(T.x[i][0], T.x[i][1]); w.y = cvt_pk_bf16(T.x[i][2], T.x[i][3]);
;         *(LAS u32x2*)(vd + ri * 64) = w;
;         if (vcopy && ri + rl >= skip) *(f32x4*)(vc + (size_t)ri * 256) = T.x[i]; }
	v_cmp_le_i32_e32 vcc, v0, v167
	v_cmp_gt_i32_e64 s[40:41], v0, v150
	s_or_b64 vcc, vcc, s[40:41]
	v_add_u32_e32 v0, 18, v164
	v_cndmask_b32_e32 v55, v59, v219, vcc
	v_cmp_gt_i32_e32 vcc, v0, v167
	v_cmp_le_i32_e64 s[40:41], v0, v150
	s_and_b64 vcc, vcc, s[40:41]
	v_add_u32_e32 v0, 50, v164
	v_cndmask_b32_e32 v52, v219, v44, vcc
	v_cmp_le_i32_e32 vcc, v0, v167
	v_cmp_gt_i32_e64 s[40:41], v0, v150
	s_or_b64 vcc, vcc, s[40:41]
	v_add_u32_e32 v0, 19, v164
	v_cndmask_b32_e32 v53, v60, v219, vcc
	v_cmp_gt_i32_e32 vcc, v0, v167
	v_cmp_le_i32_e64 s[40:41], v0, v150
	s_and_b64 vcc, vcc, s[40:41]
	v_add_u32_e32 v0, 51, v164
	v_cndmask_b32_e32 v50, v219, v45, vcc
	v_cmp_le_i32_e32 vcc, v0, v167
	v_cmp_gt_i32_e64 s[40:41], v0, v150
	s_or_b64 vcc, vcc, s[40:41]
	v_add_u32_e32 v0, 24, v164
	v_cndmask_b32_e32 v51, v61, v219, vcc
	v_cmp_gt_i32_e32 vcc, v0, v167
	v_cmp_le_i32_e64 s[40:41], v0, v150
	s_and_b64 vcc, vcc, s[40:41]
	v_add_u32_e32 v0, 56, v164
	v_cndmask_b32_e32 v44, v219, v46, vcc
	v_cmp_le_i32_e32 vcc, v0, v167
	v_cmp_gt_i32_e64 s[40:41], v0, v150
	s_or_b64 vcc, vcc, s[40:41]
	v_add_u32_e32 v0, 25, v164
	v_cndmask_b32_e32 v45, v62, v219, vcc
	v_cmp_gt_i32_e32 vcc, v0, v167
	v_cmp_le_i32_e64 s[40:41], v0, v150
	s_and_b64 vcc, vcc, s[40:41]
	v_add_u32_e32 v0, 57, v164
	v_cndmask_b32_e32 v42, v219, v47, vcc
	v_cmp_le_i32_e32 vcc, v0, v167
	v_cmp_gt_i32_e64 s[40:41], v0, v150
	s_or_b64 vcc, vcc, s[40:41]
	v_add_u32_e32 v0, 26, v164
	v_cndmask_b32_e32 v43, v63, v219, vcc
	v_cmp_gt_i32_e32 vcc, v0, v167
	v_cmp_le_i32_e64 s[40:41], v0, v150
	s_and_b64 vcc, vcc, s[40:41]
	v_add_u32_e32 v0, 58, v164
	v_cndmask_b32_e32 v38, v219, v48, vcc
	v_cmp_le_i32_e32 vcc, v0, v167
	v_cmp_gt_i32_e64 s[40:41], v0, v150
	s_or_b64 vcc, vcc, s[40:41]
	v_add_u32_e32 v0, 27, v164
	v_cndmask_b32_e32 v40, v64, v219, vcc
	v_cmp_gt_i32_e32 vcc, v0, v167
	v_cmp_le_i32_e64 s[40:41], v0, v150
	s_and_b64 vcc, vcc, s[40:41]
	v_add_u32_e32 v0, 59, v164
	v_cndmask_b32_e32 v39, v219, v49, vcc
	v_cmp_le_i32_e32 vcc, v0, v167
	v_cmp_gt_i32_e64 s[40:41], v0, v150
	v_max_f32_e32 v0, v176, v176
	v_max_f32_e32 v34, v175, v175
	v_max_f32_e32 v0, v34, v0
	v_max_f32_e32 v34, v174, v174
	v_max_f32_e32 v35, v172, v172
	v_max_f32_e32 v34, v35, v34
	v_max_f32_e32 v35, v171, v171
	v_max_f32_e32 v36, v170, v170
	v_max3_f32 v0, v173, v177, v0
	v_max_f32_e32 v35, v36, v35
	v_max3_f32 v0, v0, v34, v35
	v_max_f32_e32 v34, v169, v169
	v_max_f32_e32 v35, v168, v168
	v_max_f32_e32 v34, v35, v34
	v_max_f32_e32 v35, v161, v161
	v_max_f32_e32 v36, v159, v159
	v_max_f32_e32 v35, v36, v35
	v_max3_f32 v0, v0, v34, v35
	v_max_f32_e32 v34, v157, v157
	v_max_f32_e32 v35, v156, v156
	v_max_f32_e32 v34, v35, v34
	v_max_f32_e32 v35, v155, v155
	v_max_f32_e32 v36, v154, v154
	v_max_f32_e32 v35, v36, v35
	v_max3_f32 v0, v0, v34, v35
	v_max_f32_e32 v34, v57, v57
	v_max_f32_e32 v35, v56, v56
	v_max_f32_e32 v34, v35, v34
	v_max_f32_e32 v35, v55, v55
	v_max_f32_e32 v36, v54, v54
	v_max_f32_e32 v35, v36, v35
	v_max3_f32 v0, v0, v34, v35
	v_max_f32_e32 v34, v53, v53
	v_max_f32_e32 v35, v52, v52
	v_max_f32_e32 v34, v35, v34
	v_max_f32_e32 v35, v51, v51
	v_max_f32_e32 v36, v50, v50
	v_max_f32_e32 v35, v36, v35
	v_max3_f32 v0, v0, v34, v35
	v_max_f32_e32 v34, v45, v45
	v_max_f32_e32 v35, v44, v44
	v_max_f32_e32 v34, v35, v34
	v_max_f32_e32 v35, v43, v43
	v_max_f32_e32 v36, v42, v42
	s_or_b64 vcc, vcc, s[40:41]
	v_max_f32_e32 v35, v36, v35
	v_cndmask_b32_e32 v41, v65, v219, vcc
	v_max3_f32 v0, v0, v34, v35
	v_max_f32_e32 v34, v40, v40
	v_max_f32_e32 v35, v38, v38
	v_max_f32_e32 v34, v35, v34
	v_max_f32_e32 v35, v41, v41
	v_max_f32_e32 v36, v39, v39
	v_max_f32_e32 v35, v36, v35
	v_max3_f32 v46, v0, v34, v35
	v_lshlrev_b32_e32 v0, 9, v158
	v_and_b32_e32 v0, 0x1000, v0
	v_lshlrev_b32_e32 v34, 6, v152
	v_add3_u32 v0, s33, v0, v34
	v_and_b32_e32 v34, 56, v160
	v_add_u32_e32 v48, v0, v34
	v_lshl_add_u64 v[34:35], s[96:97], 0, v[82:83]
	v_lshlrev_b32_e32 v0, 2, v178
	v_mov_b32_e32 v47, v46
	v_lshl_add_u64 v[36:37], v[34:35], 0, v[0:1]
	s_nop 0
	v_permlane32_swap_b32_e32 v46, v47
	v_lshl_add_u64 v[34:35], v[36:37], 0, s[2:3]
	s_waitcnt vmcnt(15)
	v_cvt_pk_bf16_f32 v58, v122, v123
	v_cvt_pk_bf16_f32 v59, v124, v125
	ds_write_b64 v48, v[58:59] offset:8192
	s_and_saveexec_b64 s[2:3], s[6:7]
	s_cbranch_execz .LBB0_1342
	global_store_dwordx4 v[34:35], v[122:125], off nt
.LBB0_1342:
	s_or_b64 exec, exec, s[2:3]
	s_waitcnt vmcnt(9)
	v_cvt_pk_bf16_f32 v58, v134, v135
	v_cvt_pk_bf16_f32 v59, v136, v137
	ds_write_b64 v48, v[58:59] offset:8448
	s_and_saveexec_b64 s[2:3], s[8:9]
	s_cbranch_execz .LBB0_1344
	global_store_dwordx4 v[36:37], v[134:137], off nt
.LBB0_1344:
	s_or_b64 exec, exec, s[2:3]
	v_cvt_pk_bf16_f32 v36, v110, v111
	v_cvt_pk_bf16_f32 v37, v112, v113
	ds_write_b64 v48, v[36:37] offset:8704
	s_and_saveexec_b64 s[2:3], s[10:11]
	s_cbranch_execz .LBB0_1346
	v_add_co_u32_e32 v36, vcc, 0x2000, v34
	s_nop 1
	v_addc_co_u32_e32 v37, vcc, 0, v35, vcc
	global_store_dwordx4 v[36:37], v[110:113], off nt
; #define LAS __attribute__((address_space(3)))
; __device__ __forceinline__ unsigned cvt_pk_bf16(float lo, float hi) { unsigned r; asm volatile("v_cvt_pk_bf16_f32 %0, %1, %2" : "=v"(r) : "v"(lo), "v"(hi)); return r; }
; __device__ __forceinline__ void f32_v_commit(const F32Half& T, LAS unsigned char* vb, int lane, float* vcopy, int skip, int h) {
;     const int pc = lane & 15, rl = lane >> 4;
;     LAS unsigned char* vd = vb + (pc >> 3) * 4096 + rl * 64 + (pc & 7) * 8; float* vc = vcopy + (size_t)rl * 256 + pc * 4;
; #pragma unroll
;     for (int i = 0; i < 8; ++i) { const int ri = 4 * (8 * h + i); u32x2 w; w.x = cvt_pk_bf16(T.x[i][0], T.x[i][1]); w.y = cvt_pk_bf16(T.x[i][2], T.x[i][3]);
;         *(LAS u32x2*)(vd + ri * 64) = w;
;         if (vcopy && ri + rl >= skip) *(f32x4*)(vc + (size_t)ri * 256) = T.x[i]; }
; }
.LBB0_1346:
	s_or_b64 exec, exec, s[2:3]
	v_cvt_pk_bf16_f32 v36, v102, v103
	v_cvt_pk_bf16_f32 v37, v104, v105
	ds_write_b64 v48, v[36:37] offset:8960
	s_and_saveexec_b64 s[2:3], s[12:13]
	s_cbranch_execz .LBB0_1348
	v_add_co_u32_e32 v36, vcc, 0x3000, v34
	s_nop 1
	v_addc_co_u32_e32 v37, vcc, 0, v35, vcc
	global_store_dwordx4 v[36:37], v[102:105], off nt
.LBB0_1348:
	s_or_b64 exec, exec, s[2:3]
	v_cvt_pk_bf16_f32 v36, v98, v99
	v_cvt_pk_bf16_f32 v37, v100, v101
	ds_write_b64 v48, v[36:37] offset:9216
	s_and_saveexec_b64 s[2:3], s[14:15]
	s_cbranch_execz .LBB0_1350
	v_add_co_u32_e32 v36, vcc, 0x4000, v34
	s_nop 1
	v_addc_co_u32_e32 v37, vcc, 0, v35, vcc
	global_store_dwordx4 v[36:37], v[98:101], off nt
.LBB0_1350:
	s_or_b64 exec, exec, s[2:3]
	v_cvt_pk_bf16_f32 v36, v94, v95
	v_cvt_pk_bf16_f32 v37, v96, v97
	ds_write_b64 v48, v[36:37] offset:9472
	s_and_saveexec_b64 s[2:3], s[16:17]
	s_cbranch_execz .LBB0_1352
	v_add_co_u32_e32 v36, vcc, 0x5000, v34
	s_nop 1
	v_addc_co_u32_e32 v37, vcc, 0, v35, vcc
	global_store_dwordx4 v[36:37], v[94:97], off nt
.LBB0_1352:
	s_or_b64 exec, exec, s[2:3]
	v_cvt_pk_bf16_f32 v36, v90, v91
	v_cvt_pk_bf16_f32 v37, v92, v93
	ds_write_b64 v48, v[36:37] offset:9728
	s_and_saveexec_b64 s[2:3], s[18:19]
	s_cbranch_execz .LBB0_1354
	v_add_co_u32_e32 v36, vcc, 0x6000, v34
	s_nop 1
	v_addc_co_u32_e32 v37, vcc, 0, v35, vcc
	global_store_dwordx4 v[36:37], v[90:93], off nt
.LBB0_1354:
	s_or_b64 exec, exec, s[2:3]
	s_waitcnt vmcnt(8)
	v_cvt_pk_bf16_f32 v36, v86, v87
	v_cvt_pk_bf16_f32 v37, v88, v89
	ds_write_b64 v48, v[36:37] offset:9984
	s_and_saveexec_b64 s[2:3], s[20:21]
	s_cbranch_execz .LBB0_1356
	v_add_co_u32_e32 v36, vcc, 0x7000, v34
	s_nop 1
	v_addc_co_u32_e32 v37, vcc, 0, v35, vcc
	global_store_dwordx4 v[36:37], v[86:89], off nt
.LBB0_1356:
	s_or_b64 exec, exec, s[2:3]
	s_waitcnt vmcnt(7)
	v_cvt_pk_bf16_f32 v36, v146, v147
	v_cvt_pk_bf16_f32 v37, v148, v149
	ds_write_b64 v48, v[36:37] offset:10240
	s_and_saveexec_b64 s[2:3], s[22:23]
	s_cbranch_execz .LBB0_1358
	v_add_co_u32_e32 v36, vcc, 0x8000, v34
	s_nop 1
	v_addc_co_u32_e32 v37, vcc, 0, v35, vcc
	global_store_dwordx4 v[36:37], v[146:149], off nt
.LBB0_1358:
	s_or_b64 exec, exec, s[2:3]
	s_waitcnt vmcnt(6)
	v_cvt_pk_bf16_f32 v36, v142, v143
	v_cvt_pk_bf16_f32 v37, v144, v145
	ds_write_b64 v48, v[36:37] offset:10496
	s_and_saveexec_b64 s[2:3], s[24:25]
	s_cbranch_execz .LBB0_1360
	v_add_co_u32_e32 v36, vcc, 0x9000, v34
	s_nop 1
	v_addc_co_u32_e32 v37, vcc, 0, v35, vcc
	global_store_dwordx4 v[36:37], v[142:145], off nt
.LBB0_1360:
	s_or_b64 exec, exec, s[2:3]
	s_waitcnt vmcnt(5)
	v_cvt_pk_bf16_f32 v36, v138, v139
	v_cvt_pk_bf16_f32 v37, v140, v141
	ds_write_b64 v48, v[36:37] offset:10752
	s_and_saveexec_b64 s[2:3], s[26:27]
	s_cbranch_execz .LBB0_1362
	v_add_co_u32_e32 v36, vcc, 0xa000, v34
	s_nop 1
	v_addc_co_u32_e32 v37, vcc, 0, v35, vcc
	global_store_dwordx4 v[36:37], v[138:141], off nt
.LBB0_1362:
	s_or_b64 exec, exec, s[2:3]
	s_waitcnt vmcnt(4)
	v_cvt_pk_bf16_f32 v36, v130, v131
	v_cvt_pk_bf16_f32 v37, v132, v133
	ds_write_b64 v48, v[36:37] offset:11008
	s_and_saveexec_b64 s[2:3], s[28:29]
	s_cbranch_execz .LBB0_1364
	v_add_co_u32_e32 v36, vcc, 0xb000, v34
	s_nop 1
	v_addc_co_u32_e32 v37, vcc, 0, v35, vcc
	global_store_dwordx4 v[36:37], v[130:133], off nt
.LBB0_1364:
	s_or_b64 exec, exec, s[2:3]
	s_waitcnt vmcnt(3)
	v_cvt_pk_bf16_f32 v36, v126, v127
	v_cvt_pk_bf16_f32 v37, v128, v129
	ds_write_b64 v48, v[36:37] offset:11264
	s_and_saveexec_b64 s[2:3], s[30:31]
	s_cbranch_execz .LBB0_1366
	v_add_co_u32_e32 v36, vcc, 0xc000, v34
	s_nop 1
	v_addc_co_u32_e32 v37, vcc, 0, v35, vcc
	global_store_dwordx4 v[36:37], v[126:129], off nt
.LBB0_1366:
	s_or_b64 exec, exec, s[2:3]
	s_waitcnt vmcnt(2)
	v_cvt_pk_bf16_f32 v36, v118, v119
	v_cvt_pk_bf16_f32 v37, v120, v121
	ds_write_b64 v48, v[36:37] offset:11520
	s_and_saveexec_b64 s[2:3], s[34:35]
	s_cbranch_execz .LBB0_1368
	v_add_co_u32_e32 v36, vcc, 0xd000, v34
	s_nop 1
	v_addc_co_u32_e32 v37, vcc, 0, v35, vcc
	global_store_dwordx4 v[36:37], v[118:121], off nt
.LBB0_1368:
	s_or_b64 exec, exec, s[2:3]
	s_waitcnt vmcnt(1)
	v_cvt_pk_bf16_f32 v36, v114, v115
	v_cvt_pk_bf16_f32 v37, v116, v117
	ds_write_b64 v48, v[36:37] offset:11776
	s_and_saveexec_b64 s[2:3], s[36:37]
	s_cbranch_execz .LBB0_1370
	v_add_co_u32_e32 v36, vcc, 0xe000, v34
	s_nop 1
	v_addc_co_u32_e32 v37, vcc, 0, v35, vcc
	global_store_dwordx4 v[36:37], v[114:117], off nt
.LBB0_1370:
	s_or_b64 exec, exec, s[2:3]
	s_waitcnt vmcnt(0)
	v_cvt_pk_bf16_f32 v36, v106, v107
	v_cvt_pk_bf16_f32 v37, v108, v109
	ds_write_b64 v48, v[36:37] offset:12032
	s_and_saveexec_b64 s[2:3], s[38:39]
	s_cbranch_execz .LBB0_1372
	v_add_co_u32_e32 v34, vcc, 0xf000, v34
	s_nop 1
	v_addc_co_u32_e32 v35, vcc, 0, v35, vcc
	global_store_dwordx4 v[34:35], v[106:109], off nt
